# all 128 s_setprio toggles around the GEMM MFMA segments removed (no priority change in the ping-pong main loops)
# speedup vs baseline: 1.0075x; 1.0049x over previous
.LBB0_283:
	ds_read_b128 v[170:173], v160
	ds_read_b128 v[174:177], v160 offset:1024
	ds_read_b128 v[178:181], v160 offset:2048
	ds_read_b128 v[182:185], v160 offset:3072
	v_add_u32_e32 v167, 0xc000, v148
	v_lshl_add_u64 v[222:223], s[0:1], 0, v[140:141]
	v_readfirstlane_b32 s5, v167
	v_add_u32_e32 v129, s61, v145
	v_add_u32_e32 v165, s63, v145
	v_add_u32_e32 v166, s64, v145
	v_lshl_add_u64 v[168:169], v[222:223], 0, s[82:83]
	s_mov_b32 m0, s5
	ds_read_b128 v[186:189], v161
	ds_read_b128 v[190:193], v161 offset:1024
	ds_read_b128 v[194:197], v129
	ds_read_b128 v[198:201], v129 offset:1024
	ds_read_b128 v[202:205], v165
	ds_read_b128 v[206:209], v165 offset:1024
	ds_read_b128 v[210:213], v166
	ds_read_b128 v[214:217], v166 offset:1024
	global_load_lds_dwordx4 v[168:169], off
	v_add_u32_e32 v168, 0xe000, v148
	v_lshl_add_u64 v[238:239], s[0:1], 0, v[142:143]
	v_readfirstlane_b32 s5, v168
	v_lshl_add_u64 v[218:219], v[238:239], 0, s[82:83]
	s_mov_b32 m0, s5
	s_nop 0
	global_load_lds_dwordx4 v[218:219], off
	s_waitcnt lgkmcnt(8)
	s_barrier
	s_waitcnt lgkmcnt(0)
	v_mfma_f32_16x16x32_bf16 v[124:127], v[186:189], v[170:173], v[124:127]
	v_mfma_f32_16x16x32_bf16 v[120:123], v[186:189], v[178:181], v[120:123]
	v_mfma_f32_16x16x32_bf16 v[116:119], v[194:197], v[170:173], v[116:119]
	v_mfma_f32_16x16x32_bf16 v[112:115], v[194:197], v[178:181], v[112:115]
	v_mfma_f32_16x16x32_bf16 v[108:111], v[202:205], v[170:173], v[108:111]
	v_mfma_f32_16x16x32_bf16 v[104:107], v[202:205], v[178:181], v[104:107]
	v_mfma_f32_16x16x32_bf16 v[100:103], v[210:213], v[170:173], v[100:103]
	v_mfma_f32_16x16x32_bf16 v[96:99], v[210:213], v[178:181], v[96:99]
	v_mfma_f32_16x16x32_bf16 v[124:127], v[190:193], v[174:177], v[124:127]
	v_mfma_f32_16x16x32_bf16 v[120:123], v[190:193], v[182:185], v[120:123]
	v_mfma_f32_16x16x32_bf16 v[116:119], v[198:201], v[174:177], v[116:119]
	v_mfma_f32_16x16x32_bf16 v[112:115], v[198:201], v[182:185], v[112:115]
	v_mfma_f32_16x16x32_bf16 v[108:111], v[206:209], v[174:177], v[108:111]
	v_mfma_f32_16x16x32_bf16 v[104:107], v[206:209], v[182:185], v[104:107]
	v_mfma_f32_16x16x32_bf16 v[100:103], v[214:217], v[174:177], v[100:103]
	v_mfma_f32_16x16x32_bf16 v[96:99], v[214:217], v[182:185], v[96:99]
	s_barrier
	v_lshl_add_u64 v[240:241], s[0:1], 0, v[136:137]
	v_readfirstlane_b32 s5, v146
	v_lshl_add_u64 v[242:243], v[240:241], 0, s[84:85]
	s_mov_b32 m0, s5
	ds_read_b128 v[218:221], v162
	ds_read_b128 v[226:229], v162 offset:1024
	ds_read_b128 v[230:233], v162 offset:2048
	ds_read_b128 v[234:237], v162 offset:3072
	global_load_lds_dwordx4 v[242:243], off
	v_lshl_add_u64 v[242:243], s[0:1], 0, v[138:139]
	v_readfirstlane_b32 s5, v147
	v_lshl_add_u64 v[244:245], v[242:243], 0, s[84:85]
	s_mov_b32 m0, s5
	s_nop 0
	global_load_lds_dwordx4 v[244:245], off
	s_barrier
	s_waitcnt lgkmcnt(0)
	v_mfma_f32_16x16x32_bf16 v[92:95], v[186:189], v[218:221], v[92:95]
	v_mfma_f32_16x16x32_bf16 v[88:91], v[186:189], v[230:233], v[88:91]
	v_mfma_f32_16x16x32_bf16 v[84:87], v[194:197], v[218:221], v[84:87]
	v_mfma_f32_16x16x32_bf16 v[80:83], v[194:197], v[230:233], v[80:83]
	v_mfma_f32_16x16x32_bf16 v[76:79], v[202:205], v[218:221], v[76:79]
	v_mfma_f32_16x16x32_bf16 v[72:75], v[202:205], v[230:233], v[72:75]
	v_mfma_f32_16x16x32_bf16 v[68:71], v[210:213], v[218:221], v[68:71]
	v_mfma_f32_16x16x32_bf16 v[64:67], v[210:213], v[230:233], v[64:67]
	v_mfma_f32_16x16x32_bf16 v[92:95], v[190:193], v[226:229], v[92:95]
	v_mfma_f32_16x16x32_bf16 v[88:91], v[190:193], v[234:237], v[88:91]
	v_mfma_f32_16x16x32_bf16 v[84:87], v[198:201], v[226:229], v[84:87]
	v_mfma_f32_16x16x32_bf16 v[80:83], v[198:201], v[234:237], v[80:83]
	v_mfma_f32_16x16x32_bf16 v[76:79], v[206:209], v[226:229], v[76:79]
	v_mfma_f32_16x16x32_bf16 v[72:75], v[206:209], v[234:237], v[72:75]
	v_mfma_f32_16x16x32_bf16 v[68:71], v[214:217], v[226:229], v[68:71]
	v_mfma_f32_16x16x32_bf16 v[64:67], v[214:217], v[234:237], v[64:67]
	v_readfirstlane_b32 s5, v148
	v_lshl_add_u64 v[244:245], v[222:223], 0, s[86:87]
	s_mov_b32 m0, s5
	v_readfirstlane_b32 s5, v149
	s_barrier
	ds_read_b128 v[186:189], v161 offset:16384
	ds_read_b128 v[190:193], v161 offset:17408
	ds_read_b128 v[194:197], v129 offset:16384
	ds_read_b128 v[198:201], v129 offset:17408
	ds_read_b128 v[202:205], v165 offset:16384
	ds_read_b128 v[206:209], v165 offset:17408
	ds_read_b128 v[210:213], v166 offset:16384
	ds_read_b128 v[214:217], v166 offset:17408
	global_load_lds_dwordx4 v[244:245], off
	v_lshl_add_u64 v[244:245], v[238:239], 0, s[86:87]
	s_mov_b32 m0, s5
	s_nop 0
	global_load_lds_dwordx4 v[244:245], off
	s_barrier
	s_waitcnt lgkmcnt(0)
	v_mfma_f32_16x16x32_bf16 v[60:63], v[186:189], v[170:173], v[60:63]
	v_mfma_f32_16x16x32_bf16 v[56:59], v[186:189], v[178:181], v[56:59]
	v_mfma_f32_16x16x32_bf16 v[52:55], v[194:197], v[170:173], v[52:55]
	v_mfma_f32_16x16x32_bf16 v[48:51], v[194:197], v[178:181], v[48:51]
	v_mfma_f32_16x16x32_bf16 v[44:47], v[202:205], v[170:173], v[44:47]
	v_mfma_f32_16x16x32_bf16 v[40:43], v[202:205], v[178:181], v[40:43]
	v_mfma_f32_16x16x32_bf16 v[36:39], v[210:213], v[170:173], v[36:39]
	v_mfma_f32_16x16x32_bf16 v[32:35], v[210:213], v[178:181], v[32:35]
	v_mfma_f32_16x16x32_bf16 v[60:63], v[190:193], v[174:177], v[60:63]
	v_mfma_f32_16x16x32_bf16 v[56:59], v[190:193], v[182:185], v[56:59]
	v_mfma_f32_16x16x32_bf16 v[52:55], v[198:201], v[174:177], v[52:55]
	v_mfma_f32_16x16x32_bf16 v[48:51], v[198:201], v[182:185], v[48:51]
	v_mfma_f32_16x16x32_bf16 v[44:47], v[206:209], v[174:177], v[44:47]
	v_mfma_f32_16x16x32_bf16 v[40:43], v[206:209], v[182:185], v[40:43]
	v_mfma_f32_16x16x32_bf16 v[36:39], v[214:217], v[174:177], v[36:39]
	v_mfma_f32_16x16x32_bf16 v[32:35], v[214:217], v[182:185], v[32:35]
	s_barrier
	v_readfirstlane_b32 s5, v150
	v_lshl_add_u64 v[170:171], v[240:241], 0, s[88:89]
	s_mov_b32 m0, s5
	v_readfirstlane_b32 s5, v151
	global_load_lds_dwordx4 v[170:171], off
	v_lshl_add_u64 v[170:171], v[242:243], 0, s[88:89]
	s_mov_b32 m0, s5
	s_nop 0
	global_load_lds_dwordx4 v[170:171], off
	s_waitcnt vmcnt(6)
	s_barrier
	v_mfma_f32_16x16x32_bf16 v[28:31], v[186:189], v[218:221], v[28:31]
	v_mfma_f32_16x16x32_bf16 v[24:27], v[186:189], v[230:233], v[24:27]
	v_mfma_f32_16x16x32_bf16 v[20:23], v[194:197], v[218:221], v[20:23]
	v_mfma_f32_16x16x32_bf16 v[16:19], v[194:197], v[230:233], v[16:19]
	v_mfma_f32_16x16x32_bf16 v[12:15], v[202:205], v[218:221], v[12:15]
	v_mfma_f32_16x16x32_bf16 v[8:11], v[202:205], v[230:233], v[8:11]
	v_mfma_f32_16x16x32_bf16 v[4:7], v[210:213], v[218:221], v[4:7]
	v_mfma_f32_16x16x32_bf16 v[0:3], v[210:213], v[230:233], v[0:3]
	v_mfma_f32_16x16x32_bf16 v[28:31], v[190:193], v[226:229], v[28:31]
	v_mfma_f32_16x16x32_bf16 v[24:27], v[190:193], v[234:237], v[24:27]
	v_mfma_f32_16x16x32_bf16 v[20:23], v[198:201], v[226:229], v[20:23]
	v_mfma_f32_16x16x32_bf16 v[16:19], v[198:201], v[234:237], v[16:19]
	v_mfma_f32_16x16x32_bf16 v[12:15], v[206:209], v[226:229], v[12:15]
	v_mfma_f32_16x16x32_bf16 v[8:11], v[206:209], v[234:237], v[8:11]
	v_mfma_f32_16x16x32_bf16 v[4:7], v[214:217], v[226:229], v[4:7]
	v_mfma_f32_16x16x32_bf16 v[0:3], v[214:217], v[234:237], v[0:3]
	s_barrier
	ds_read_b128 v[170:173], v163
	ds_read_b128 v[174:177], v163 offset:1024
	ds_read_b128 v[178:181], v163 offset:2048
	ds_read_b128 v[182:185], v163 offset:3072
	v_readfirstlane_b32 s5, v152
	v_lshl_add_u64 v[218:219], v[222:223], 0, s[90:91]
	s_mov_b32 m0, s5
	v_readfirstlane_b32 s5, v153
	ds_read_b128 v[186:189], v161 offset:32768
	ds_read_b128 v[190:193], v161 offset:33792
	ds_read_b128 v[194:197], v129 offset:32768
	ds_read_b128 v[198:201], v129 offset:33792
	ds_read_b128 v[202:205], v165 offset:32768
	ds_read_b128 v[206:209], v165 offset:33792
	ds_read_b128 v[210:213], v166 offset:32768
	ds_read_b128 v[214:217], v166 offset:33792
	global_load_lds_dwordx4 v[218:219], off
	v_lshl_add_u64 v[218:219], v[238:239], 0, s[90:91]
	s_mov_b32 m0, s5
	s_nop 0
	global_load_lds_dwordx4 v[218:219], off
	s_waitcnt lgkmcnt(8)
	s_barrier
	s_waitcnt lgkmcnt(0)
	v_mfma_f32_16x16x32_bf16 v[124:127], v[186:189], v[170:173], v[124:127]
	v_mfma_f32_16x16x32_bf16 v[120:123], v[186:189], v[178:181], v[120:123]
	v_mfma_f32_16x16x32_bf16 v[116:119], v[194:197], v[170:173], v[116:119]
	v_mfma_f32_16x16x32_bf16 v[112:115], v[194:197], v[178:181], v[112:115]
	v_mfma_f32_16x16x32_bf16 v[108:111], v[202:205], v[170:173], v[108:111]
	v_mfma_f32_16x16x32_bf16 v[104:107], v[202:205], v[178:181], v[104:107]
	v_mfma_f32_16x16x32_bf16 v[100:103], v[210:213], v[170:173], v[100:103]
	v_mfma_f32_16x16x32_bf16 v[96:99], v[210:213], v[178:181], v[96:99]
	v_mfma_f32_16x16x32_bf16 v[124:127], v[190:193], v[174:177], v[124:127]
	v_mfma_f32_16x16x32_bf16 v[120:123], v[190:193], v[182:185], v[120:123]
	v_mfma_f32_16x16x32_bf16 v[116:119], v[198:201], v[174:177], v[116:119]
	v_mfma_f32_16x16x32_bf16 v[112:115], v[198:201], v[182:185], v[112:115]
	v_mfma_f32_16x16x32_bf16 v[108:111], v[206:209], v[174:177], v[108:111]
	v_mfma_f32_16x16x32_bf16 v[104:107], v[206:209], v[182:185], v[104:107]
	v_mfma_f32_16x16x32_bf16 v[100:103], v[214:217], v[174:177], v[100:103]
	v_mfma_f32_16x16x32_bf16 v[96:99], v[214:217], v[182:185], v[96:99]
	s_barrier
	v_readfirstlane_b32 s5, v154
	v_lshl_add_u64 v[244:245], v[240:241], 0, s[92:93]
	s_mov_b32 m0, s5
	v_readfirstlane_b32 s5, v155
	ds_read_b128 v[218:221], v164
	ds_read_b128 v[226:229], v164 offset:1024
	ds_read_b128 v[230:233], v164 offset:2048
	ds_read_b128 v[234:237], v164 offset:3072
	global_load_lds_dwordx4 v[244:245], off
	v_lshl_add_u64 v[244:245], v[242:243], 0, s[92:93]
	s_mov_b32 m0, s5
	s_nop 0
	global_load_lds_dwordx4 v[244:245], off
	s_barrier
	s_waitcnt lgkmcnt(0)
	v_mfma_f32_16x16x32_bf16 v[92:95], v[186:189], v[218:221], v[92:95]
	v_mfma_f32_16x16x32_bf16 v[88:91], v[186:189], v[230:233], v[88:91]
	v_mfma_f32_16x16x32_bf16 v[84:87], v[194:197], v[218:221], v[84:87]
	v_mfma_f32_16x16x32_bf16 v[80:83], v[194:197], v[230:233], v[80:83]
	v_mfma_f32_16x16x32_bf16 v[76:79], v[202:205], v[218:221], v[76:79]
	v_mfma_f32_16x16x32_bf16 v[72:75], v[202:205], v[230:233], v[72:75]
	v_mfma_f32_16x16x32_bf16 v[68:71], v[210:213], v[218:221], v[68:71]
	v_mfma_f32_16x16x32_bf16 v[64:67], v[210:213], v[230:233], v[64:67]
	v_mfma_f32_16x16x32_bf16 v[92:95], v[190:193], v[226:229], v[92:95]
	v_mfma_f32_16x16x32_bf16 v[88:91], v[190:193], v[234:237], v[88:91]
	v_mfma_f32_16x16x32_bf16 v[84:87], v[198:201], v[226:229], v[84:87]
	v_mfma_f32_16x16x32_bf16 v[80:83], v[198:201], v[234:237], v[80:83]
	v_mfma_f32_16x16x32_bf16 v[76:79], v[206:209], v[226:229], v[76:79]
	v_mfma_f32_16x16x32_bf16 v[72:75], v[206:209], v[234:237], v[72:75]
	v_mfma_f32_16x16x32_bf16 v[68:71], v[214:217], v[226:229], v[68:71]
	v_mfma_f32_16x16x32_bf16 v[64:67], v[214:217], v[234:237], v[64:67]
	v_readfirstlane_b32 s5, v156
	v_lshl_add_u64 v[222:223], v[222:223], 0, s[94:95]
	s_mov_b32 m0, s5
	v_readfirstlane_b32 s5, v157
	s_barrier
	ds_read_b128 v[186:189], v161 offset:49152
	ds_read_b128 v[190:193], v161 offset:50176
	ds_read_b128 v[194:197], v129 offset:49152
	ds_read_b128 v[198:201], v129 offset:50176
	ds_read_b128 v[202:205], v165 offset:49152
	ds_read_b128 v[206:209], v165 offset:50176
	ds_read_b128 v[210:213], v166 offset:49152
	ds_read_b128 v[214:217], v166 offset:50176
	global_load_lds_dwordx4 v[222:223], off
	v_lshl_add_u64 v[222:223], v[238:239], 0, s[94:95]
	s_mov_b32 m0, s5
	s_nop 0
	global_load_lds_dwordx4 v[222:223], off
	s_barrier
	s_waitcnt lgkmcnt(0)
	v_mfma_f32_16x16x32_bf16 v[60:63], v[186:189], v[170:173], v[60:63]
	v_mfma_f32_16x16x32_bf16 v[56:59], v[186:189], v[178:181], v[56:59]
	v_mfma_f32_16x16x32_bf16 v[52:55], v[194:197], v[170:173], v[52:55]
	v_mfma_f32_16x16x32_bf16 v[48:51], v[194:197], v[178:181], v[48:51]
	v_mfma_f32_16x16x32_bf16 v[44:47], v[202:205], v[170:173], v[44:47]
	v_mfma_f32_16x16x32_bf16 v[40:43], v[202:205], v[178:181], v[40:43]
	v_mfma_f32_16x16x32_bf16 v[36:39], v[210:213], v[170:173], v[36:39]
	v_mfma_f32_16x16x32_bf16 v[32:35], v[210:213], v[178:181], v[32:35]
	v_mfma_f32_16x16x32_bf16 v[60:63], v[190:193], v[174:177], v[60:63]
	v_mfma_f32_16x16x32_bf16 v[56:59], v[190:193], v[182:185], v[56:59]
	v_mfma_f32_16x16x32_bf16 v[52:55], v[198:201], v[174:177], v[52:55]
	v_mfma_f32_16x16x32_bf16 v[48:51], v[198:201], v[182:185], v[48:51]
	v_mfma_f32_16x16x32_bf16 v[44:47], v[206:209], v[174:177], v[44:47]
	v_mfma_f32_16x16x32_bf16 v[40:43], v[206:209], v[182:185], v[40:43]
	v_mfma_f32_16x16x32_bf16 v[36:39], v[214:217], v[174:177], v[36:39]
	v_mfma_f32_16x16x32_bf16 v[32:35], v[214:217], v[182:185], v[32:35]
	s_barrier
	v_readfirstlane_b32 s5, v158
	v_lshl_add_u64 v[170:171], v[240:241], 0, s[96:97]
	s_mov_b32 m0, s5
	v_readfirstlane_b32 s5, v159
	global_load_lds_dwordx4 v[170:171], off
	v_lshl_add_u64 v[170:171], v[242:243], 0, s[96:97]
	s_mov_b32 m0, s5
	s_nop 0
	global_load_lds_dwordx4 v[170:171], off
	s_waitcnt vmcnt(6)
	s_barrier
	v_mfma_f32_16x16x32_bf16 v[28:31], v[186:189], v[218:221], v[28:31]
	v_mfma_f32_16x16x32_bf16 v[24:27], v[186:189], v[230:233], v[24:27]
	v_mfma_f32_16x16x32_bf16 v[20:23], v[194:197], v[218:221], v[20:23]
	v_mfma_f32_16x16x32_bf16 v[16:19], v[194:197], v[230:233], v[16:19]
	v_mfma_f32_16x16x32_bf16 v[12:15], v[202:205], v[218:221], v[12:15]
	v_mfma_f32_16x16x32_bf16 v[8:11], v[202:205], v[230:233], v[8:11]
	v_mfma_f32_16x16x32_bf16 v[4:7], v[210:213], v[218:221], v[4:7]
	v_mfma_f32_16x16x32_bf16 v[0:3], v[210:213], v[230:233], v[0:3]
	v_mfma_f32_16x16x32_bf16 v[28:31], v[190:193], v[226:229], v[28:31]
	v_mfma_f32_16x16x32_bf16 v[24:27], v[190:193], v[234:237], v[24:27]
	v_mfma_f32_16x16x32_bf16 v[20:23], v[198:201], v[226:229], v[20:23]
	v_mfma_f32_16x16x32_bf16 v[16:19], v[198:201], v[234:237], v[16:19]
	v_mfma_f32_16x16x32_bf16 v[12:15], v[206:209], v[226:229], v[12:15]
	v_mfma_f32_16x16x32_bf16 v[8:11], v[206:209], v[234:237], v[8:11]
	v_mfma_f32_16x16x32_bf16 v[4:7], v[214:217], v[226:229], v[4:7]
	v_mfma_f32_16x16x32_bf16 v[0:3], v[214:217], v[234:237], v[0:3]
	s_add_i32 s4, s4, 2
	s_add_u32 s0, s0, 0x100
	s_addc_u32 s1, s1, 0
	s_cmp_lt_u32 s4, 28
	s_barrier
	s_cbranch_scc1 .LBB0_283
	v_readfirstlane_b32 s0, v167
	v_lshl_add_u64 v[134:135], v[134:135], 0, s[34:35]
	s_mov_b32 m0, s0
	v_readfirstlane_b32 s0, v168
	ds_read_b128 v[136:139], v160
	ds_read_b128 v[140:143], v160 offset:1024
	ds_read_b128 v[170:173], v160 offset:2048
	ds_read_b128 v[174:177], v160 offset:3072
	ds_read_b128 v[178:181], v161
	ds_read_b128 v[182:185], v161 offset:1024
	ds_read_b128 v[186:189], v129
	ds_read_b128 v[190:193], v129 offset:1024
	ds_read_b128 v[194:197], v165
	ds_read_b128 v[198:201], v165 offset:1024
	ds_read_b128 v[202:205], v166
	ds_read_b128 v[206:209], v166 offset:1024
	global_load_lds_dwordx4 v[134:135], off
	v_lshl_add_u64 v[132:133], v[132:133], 0, s[34:35]
	s_mov_b32 m0, s0
	s_nop 0
	global_load_lds_dwordx4 v[132:133], off
	s_barrier
	s_waitcnt lgkmcnt(0)
	v_mfma_f32_16x16x32_bf16 v[124:127], v[178:181], v[136:139], v[124:127]
	v_mfma_f32_16x16x32_bf16 v[120:123], v[178:181], v[170:173], v[120:123]
	v_mfma_f32_16x16x32_bf16 v[116:119], v[186:189], v[136:139], v[116:119]
	v_mfma_f32_16x16x32_bf16 v[112:115], v[186:189], v[170:173], v[112:115]
	v_mfma_f32_16x16x32_bf16 v[124:127], v[182:185], v[140:143], v[124:127]
	v_mfma_f32_16x16x32_bf16 v[120:123], v[182:185], v[174:177], v[120:123]
	v_mfma_f32_16x16x32_bf16 v[116:119], v[190:193], v[140:143], v[116:119]
	v_mfma_f32_16x16x32_bf16 v[112:115], v[190:193], v[174:177], v[112:115]
	v_mfma_f32_16x16x32_bf16 v[108:111], v[194:197], v[136:139], v[108:111]
	v_mfma_f32_16x16x32_bf16 v[104:107], v[194:197], v[170:173], v[104:107]
	v_mfma_f32_16x16x32_bf16 v[100:103], v[202:205], v[136:139], v[100:103]
	v_mfma_f32_16x16x32_bf16 v[96:99], v[202:205], v[170:173], v[96:99]
	v_mfma_f32_16x16x32_bf16 v[132:135], v[198:201], v[140:143], v[108:111]
	v_mfma_f32_16x16x32_bf16 v[210:213], v[198:201], v[174:177], v[104:107]
	v_mfma_f32_16x16x32_bf16 v[214:217], v[206:209], v[140:143], v[100:103]
	v_mfma_f32_16x16x32_bf16 v[218:221], v[206:209], v[174:177], v[96:99]
	s_barrier
	s_nop 1
	ds_read_b128 v[96:99], v162
	ds_read_b128 v[100:103], v162 offset:1024
	ds_read_b128 v[104:107], v162 offset:2048
	ds_read_b128 v[108:111], v162 offset:3072
	s_barrier
	s_waitcnt lgkmcnt(0)
	v_mfma_f32_16x16x32_bf16 v[92:95], v[178:181], v[96:99], v[92:95]
	v_mfma_f32_16x16x32_bf16 v[88:91], v[178:181], v[104:107], v[88:91]
	v_mfma_f32_16x16x32_bf16 v[84:87], v[186:189], v[96:99], v[84:87]
	v_mfma_f32_16x16x32_bf16 v[80:83], v[186:189], v[104:107], v[80:83]
	v_mfma_f32_16x16x32_bf16 v[92:95], v[182:185], v[100:103], v[92:95]
	v_mfma_f32_16x16x32_bf16 v[88:91], v[182:185], v[108:111], v[88:91]
	v_mfma_f32_16x16x32_bf16 v[84:87], v[190:193], v[100:103], v[84:87]
	v_mfma_f32_16x16x32_bf16 v[80:83], v[190:193], v[108:111], v[80:83]
	v_mfma_f32_16x16x32_bf16 v[76:79], v[194:197], v[96:99], v[76:79]
	v_mfma_f32_16x16x32_bf16 v[72:75], v[194:197], v[104:107], v[72:75]
	v_mfma_f32_16x16x32_bf16 v[68:71], v[202:205], v[96:99], v[68:71]
	v_mfma_f32_16x16x32_bf16 v[64:67], v[202:205], v[104:107], v[64:67]
	v_mfma_f32_16x16x32_bf16 v[178:181], v[198:201], v[100:103], v[76:79]
	v_mfma_f32_16x16x32_bf16 v[182:185], v[198:201], v[108:111], v[72:75]
	v_mfma_f32_16x16x32_bf16 v[186:189], v[206:209], v[100:103], v[68:71]
	v_mfma_f32_16x16x32_bf16 v[190:193], v[206:209], v[108:111], v[64:67]
	s_barrier
	s_nop 1
	ds_read_b128 v[64:67], v161 offset:16384
	ds_read_b128 v[68:71], v161 offset:17408
	ds_read_b128 v[72:75], v129 offset:16384
	ds_read_b128 v[76:79], v129 offset:17408
	ds_read_b128 v[194:197], v165 offset:16384
	ds_read_b128 v[198:201], v165 offset:17408
	ds_read_b128 v[202:205], v166 offset:16384
	ds_read_b128 v[206:209], v166 offset:17408
	s_waitcnt vmcnt(4)
	s_barrier
	s_waitcnt lgkmcnt(0)
	v_mfma_f32_16x16x32_bf16 v[60:63], v[64:67], v[136:139], v[60:63]
	v_mfma_f32_16x16x32_bf16 v[56:59], v[64:67], v[170:173], v[56:59]
	v_mfma_f32_16x16x32_bf16 v[52:55], v[72:75], v[136:139], v[52:55]
	v_mfma_f32_16x16x32_bf16 v[48:51], v[72:75], v[170:173], v[48:51]
	v_mfma_f32_16x16x32_bf16 v[60:63], v[68:71], v[140:143], v[60:63]
	v_mfma_f32_16x16x32_bf16 v[56:59], v[68:71], v[174:177], v[56:59]
	v_mfma_f32_16x16x32_bf16 v[52:55], v[76:79], v[140:143], v[52:55]
	v_mfma_f32_16x16x32_bf16 v[48:51], v[76:79], v[174:177], v[48:51]
	v_mfma_f32_16x16x32_bf16 v[44:47], v[194:197], v[136:139], v[44:47]
	v_mfma_f32_16x16x32_bf16 v[40:43], v[194:197], v[170:173], v[40:43]
	v_mfma_f32_16x16x32_bf16 v[36:39], v[202:205], v[136:139], v[36:39]
	v_mfma_f32_16x16x32_bf16 v[32:35], v[202:205], v[170:173], v[32:35]
	v_mfma_f32_16x16x32_bf16 v[226:229], v[198:201], v[140:143], v[44:47]
	v_mfma_f32_16x16x32_bf16 v[230:233], v[198:201], v[174:177], v[40:43]
	v_mfma_f32_16x16x32_bf16 v[136:139], v[206:209], v[140:143], v[36:39]
	v_mfma_f32_16x16x32_bf16 v[140:143], v[206:209], v[174:177], v[32:35]
	v_mfma_f32_16x16x32_bf16 v[28:31], v[64:67], v[96:99], v[28:31]
	v_mfma_f32_16x16x32_bf16 v[24:27], v[64:67], v[104:107], v[24:27]
	v_mfma_f32_16x16x32_bf16 v[20:23], v[72:75], v[96:99], v[20:23]
	v_mfma_f32_16x16x32_bf16 v[16:19], v[72:75], v[104:107], v[16:19]
	v_mfma_f32_16x16x32_bf16 v[28:31], v[68:71], v[100:103], v[28:31]
	v_mfma_f32_16x16x32_bf16 v[24:27], v[68:71], v[108:111], v[24:27]
	v_mfma_f32_16x16x32_bf16 v[20:23], v[76:79], v[100:103], v[20:23]
	v_mfma_f32_16x16x32_bf16 v[16:19], v[76:79], v[108:111], v[16:19]
	v_mfma_f32_16x16x32_bf16 v[12:15], v[194:197], v[96:99], v[12:15]
	v_mfma_f32_16x16x32_bf16 v[8:11], v[194:197], v[104:107], v[8:11]
	v_mfma_f32_16x16x32_bf16 v[4:7], v[202:205], v[96:99], v[4:7]
	v_mfma_f32_16x16x32_bf16 v[0:3], v[202:205], v[104:107], v[0:3]
	v_mfma_f32_16x16x32_bf16 v[168:171], v[198:201], v[100:103], v[12:15]
	v_mfma_f32_16x16x32_bf16 v[172:175], v[198:201], v[108:111], v[8:11]
	v_mfma_f32_16x16x32_bf16 v[194:197], v[206:209], v[100:103], v[4:7]
	v_mfma_f32_16x16x32_bf16 v[198:201], v[206:209], v[108:111], v[0:3]
	s_barrier
	s_nop 1
	ds_read_b128 v[0:3], v163
	ds_read_b128 v[4:7], v163 offset:1024
	ds_read_b128 v[202:205], v163 offset:2048
	ds_read_b128 v[206:209], v163 offset:3072
	ds_read_b128 v[8:11], v161 offset:32768
	ds_read_b128 v[12:15], v161 offset:33792
	ds_read_b128 v[32:35], v129 offset:32768
	ds_read_b128 v[36:39], v129 offset:33792
	ds_read_b128 v[40:43], v165 offset:32768
	ds_read_b128 v[44:47], v165 offset:33792
	ds_read_b128 v[234:237], v166 offset:32768
	ds_read_b128 v[238:241], v166 offset:33792
	s_waitcnt vmcnt(2)
	s_barrier
	s_waitcnt lgkmcnt(0)
	v_mfma_f32_16x16x32_bf16 v[64:67], v[8:11], v[0:3], v[124:127]
	v_mfma_f32_16x16x32_bf16 v[104:107], v[12:15], v[4:7], v[64:67]
	v_mfma_f32_16x16x32_bf16 v[64:67], v[8:11], v[202:205], v[120:123]
	v_mfma_f32_16x16x32_bf16 v[108:111], v[12:15], v[206:209], v[64:67]
	v_mfma_f32_16x16x32_bf16 v[64:67], v[32:35], v[0:3], v[116:119]
	v_mfma_f32_16x16x32_bf16 v[96:99], v[36:39], v[4:7], v[64:67]
	v_mfma_f32_16x16x32_bf16 v[64:67], v[32:35], v[202:205], v[112:115]
	v_mfma_f32_16x16x32_bf16 v[100:103], v[36:39], v[206:209], v[64:67]
	v_mfma_f32_16x16x32_bf16 v[64:67], v[40:43], v[0:3], v[132:135]
	v_mfma_f32_16x16x32_bf16 v[72:75], v[44:47], v[4:7], v[64:67]
	v_mfma_f32_16x16x32_bf16 v[64:67], v[40:43], v[202:205], v[210:213]
	v_mfma_f32_16x16x32_bf16 v[76:79], v[44:47], v[206:209], v[64:67]
	v_mfma_f32_16x16x32_bf16 v[64:67], v[234:237], v[0:3], v[214:217]
	v_mfma_f32_16x16x32_bf16 v[68:71], v[234:237], v[202:205], v[218:221]
	v_mfma_f32_16x16x32_bf16 v[64:67], v[238:241], v[4:7], v[64:67]
	v_mfma_f32_16x16x32_bf16 v[68:71], v[238:241], v[206:209], v[68:71]
	s_barrier
	ds_read_b128 v[132:135], v164
	ds_read_b128 v[210:213], v164 offset:1024
	ds_read_b128 v[214:217], v164 offset:2048
	ds_read_b128 v[218:221], v164 offset:3072
	s_waitcnt vmcnt(0)
	s_barrier
	s_waitcnt lgkmcnt(0)
	v_mfma_f32_16x16x32_bf16 v[92:95], v[8:11], v[132:135], v[92:95]
	v_mfma_f32_16x16x32_bf16 v[8:11], v[8:11], v[214:217], v[88:91]
	v_mfma_f32_16x16x32_bf16 v[124:127], v[12:15], v[218:221], v[8:11]
	v_mfma_f32_16x16x32_bf16 v[8:11], v[32:35], v[132:135], v[84:87]
	v_mfma_f32_16x16x32_bf16 v[112:115], v[36:39], v[210:213], v[8:11]
	v_mfma_f32_16x16x32_bf16 v[8:11], v[32:35], v[214:217], v[80:83]
	v_mfma_f32_16x16x32_bf16 v[116:119], v[36:39], v[218:221], v[8:11]
	v_mfma_f32_16x16x32_bf16 v[8:11], v[40:43], v[132:135], v[178:181]
	v_mfma_f32_16x16x32_bf16 v[88:91], v[44:47], v[210:213], v[8:11]
	v_mfma_f32_16x16x32_bf16 v[8:11], v[40:43], v[214:217], v[182:185]
	v_mfma_f32_16x16x32_bf16 v[120:123], v[12:15], v[210:213], v[92:95]
	v_mfma_f32_16x16x32_bf16 v[92:95], v[44:47], v[218:221], v[8:11]
	v_mfma_f32_16x16x32_bf16 v[8:11], v[234:237], v[132:135], v[186:189]
	v_mfma_f32_16x16x32_bf16 v[80:83], v[238:241], v[210:213], v[8:11]
	v_mfma_f32_16x16x32_bf16 v[8:11], v[234:237], v[214:217], v[190:193]
	v_mfma_f32_16x16x32_bf16 v[84:87], v[238:241], v[218:221], v[8:11]
	s_barrier
	ds_read_b128 v[176:179], v161 offset:49152
	ds_read_b128 v[180:183], v161 offset:50176
	ds_read_b128 v[184:187], v129 offset:49152
	ds_read_b128 v[188:191], v129 offset:50176
	ds_read_b128 v[234:237], v165 offset:49152
	ds_read_b128 v[238:241], v165 offset:50176
	ds_read_b128 v[242:245], v166 offset:49152
	ds_read_b128 v[246:249], v166 offset:50176
	s_barrier
	s_waitcnt lgkmcnt(0)
	v_mfma_f32_16x16x32_bf16 v[8:11], v[176:179], v[0:3], v[60:63]
	v_mfma_f32_16x16x32_bf16 v[40:43], v[180:183], v[4:7], v[8:11]
	v_mfma_f32_16x16x32_bf16 v[8:11], v[176:179], v[202:205], v[56:59]
	v_mfma_f32_16x16x32_bf16 v[44:47], v[180:183], v[206:209], v[8:11]
	v_mfma_f32_16x16x32_bf16 v[8:11], v[184:187], v[0:3], v[52:55]
	v_mfma_f32_16x16x32_bf16 v[32:35], v[188:191], v[4:7], v[8:11]
	v_mfma_f32_16x16x32_bf16 v[8:11], v[184:187], v[202:205], v[48:51]
	v_mfma_f32_16x16x32_bf16 v[36:39], v[188:191], v[206:209], v[8:11]
	v_mfma_f32_16x16x32_bf16 v[8:11], v[234:237], v[0:3], v[226:229]
	v_mfma_f32_16x16x32_bf16 v[0:3], v[242:245], v[0:3], v[136:139]
	v_mfma_f32_16x16x32_bf16 v[8:11], v[238:241], v[4:7], v[8:11]
	v_mfma_f32_16x16x32_bf16 v[12:15], v[234:237], v[202:205], v[230:233]
	v_mfma_f32_16x16x32_bf16 v[0:3], v[246:249], v[4:7], v[0:3]
	v_mfma_f32_16x16x32_bf16 v[4:7], v[242:245], v[202:205], v[140:143]
	v_mfma_f32_16x16x32_bf16 v[12:15], v[238:241], v[206:209], v[12:15]
	v_mfma_f32_16x16x32_bf16 v[4:7], v[246:249], v[206:209], v[4:7]
	v_mfma_f32_16x16x32_bf16 v[16:19], v[184:187], v[214:217], v[16:19]
	v_mfma_f32_16x16x32_bf16 v[24:27], v[176:179], v[214:217], v[24:27]
	v_mfma_f32_16x16x32_bf16 v[52:55], v[188:191], v[218:221], v[16:19]
	v_mfma_f32_16x16x32_bf16 v[16:19], v[234:237], v[132:135], v[168:171]
	v_mfma_f32_16x16x32_bf16 v[28:31], v[176:179], v[132:135], v[28:31]
	v_mfma_f32_16x16x32_bf16 v[60:63], v[180:183], v[218:221], v[24:27]
	v_mfma_f32_16x16x32_bf16 v[20:23], v[184:187], v[132:135], v[20:23]
	v_mfma_f32_16x16x32_bf16 v[24:27], v[238:241], v[210:213], v[16:19]
	v_mfma_f32_16x16x32_bf16 v[16:19], v[234:237], v[214:217], v[172:175]
	v_mfma_f32_16x16x32_bf16 v[56:59], v[180:183], v[210:213], v[28:31]
	v_mfma_f32_16x16x32_bf16 v[48:51], v[188:191], v[210:213], v[20:23]
	v_mfma_f32_16x16x32_bf16 v[28:31], v[238:241], v[218:221], v[16:19]
	v_mfma_f32_16x16x32_bf16 v[16:19], v[242:245], v[132:135], v[194:197]
	v_mfma_f32_16x16x32_bf16 v[20:23], v[242:245], v[214:217], v[198:201]
	v_mfma_f32_16x16x32_bf16 v[16:19], v[246:249], v[210:213], v[16:19]
	v_mfma_f32_16x16x32_bf16 v[20:23], v[246:249], v[218:221], v[20:23]
	s_andn2_b64 vcc, exec, s[40:41]
	s_barrier
	s_cbranch_vccnz .LBB0_286
	s_barrier

.LBB0_921:
	ds_read_b128 v[170:173], v162
	ds_read_b128 v[174:177], v162 offset:1024
	ds_read_b128 v[178:181], v162 offset:2048
	ds_read_b128 v[182:185], v162 offset:3072
	v_add_u32_e32 v167, 0xc000, v150
	v_lshl_add_u64 v[222:223], s[22:23], 0, v[142:143]
	v_readfirstlane_b32 s19, v167
	v_add_u32_e32 v129, s60, v147
	v_add_u32_e32 v131, s62, v147
	v_add_u32_e32 v132, s63, v147
	v_lshl_add_u64 v[168:169], v[222:223], 0, s[10:11]
	s_mov_b32 m0, s19
	ds_read_b128 v[186:189], v163
	ds_read_b128 v[190:193], v163 offset:1024
	ds_read_b128 v[194:197], v129
	ds_read_b128 v[198:201], v129 offset:1024
	ds_read_b128 v[202:205], v131
	ds_read_b128 v[206:209], v131 offset:1024
	ds_read_b128 v[210:213], v132
	ds_read_b128 v[214:217], v132 offset:1024
	global_load_lds_dwordx4 v[168:169], off
	v_add_u32_e32 v168, 0xe000, v150
	v_lshl_add_u64 v[238:239], s[22:23], 0, v[144:145]
	v_readfirstlane_b32 s19, v168
	v_lshl_add_u64 v[218:219], v[238:239], 0, s[10:11]
	s_mov_b32 m0, s19
	s_nop 0
	global_load_lds_dwordx4 v[218:219], off
	s_waitcnt lgkmcnt(8)
	s_barrier
	s_waitcnt lgkmcnt(0)
	v_mfma_f32_16x16x32_bf16 v[124:127], v[186:189], v[170:173], v[124:127]
	v_mfma_f32_16x16x32_bf16 v[120:123], v[186:189], v[178:181], v[120:123]
	v_mfma_f32_16x16x32_bf16 v[116:119], v[194:197], v[170:173], v[116:119]
	v_mfma_f32_16x16x32_bf16 v[112:115], v[194:197], v[178:181], v[112:115]
	v_mfma_f32_16x16x32_bf16 v[108:111], v[202:205], v[170:173], v[108:111]
	v_mfma_f32_16x16x32_bf16 v[104:107], v[202:205], v[178:181], v[104:107]
	v_mfma_f32_16x16x32_bf16 v[100:103], v[210:213], v[170:173], v[100:103]
	v_mfma_f32_16x16x32_bf16 v[96:99], v[210:213], v[178:181], v[96:99]
	v_mfma_f32_16x16x32_bf16 v[124:127], v[190:193], v[174:177], v[124:127]
	v_mfma_f32_16x16x32_bf16 v[120:123], v[190:193], v[182:185], v[120:123]
	v_mfma_f32_16x16x32_bf16 v[116:119], v[198:201], v[174:177], v[116:119]
	v_mfma_f32_16x16x32_bf16 v[112:115], v[198:201], v[182:185], v[112:115]
	v_mfma_f32_16x16x32_bf16 v[108:111], v[206:209], v[174:177], v[108:111]
	v_mfma_f32_16x16x32_bf16 v[104:107], v[206:209], v[182:185], v[104:107]
	v_mfma_f32_16x16x32_bf16 v[100:103], v[214:217], v[174:177], v[100:103]
	v_mfma_f32_16x16x32_bf16 v[96:99], v[214:217], v[182:185], v[96:99]
	s_barrier
	v_lshl_add_u64 v[240:241], s[22:23], 0, v[138:139]
	v_readfirstlane_b32 s19, v148
	v_lshl_add_u64 v[242:243], v[240:241], 0, s[12:13]
	s_mov_b32 m0, s19
	ds_read_b128 v[218:221], v164
	ds_read_b128 v[226:229], v164 offset:1024
	ds_read_b128 v[230:233], v164 offset:2048
	ds_read_b128 v[234:237], v164 offset:3072
	global_load_lds_dwordx4 v[242:243], off
	v_lshl_add_u64 v[242:243], s[22:23], 0, v[140:141]
	v_readfirstlane_b32 s19, v149
	v_lshl_add_u64 v[244:245], v[242:243], 0, s[12:13]
	s_mov_b32 m0, s19
	s_nop 0
	global_load_lds_dwordx4 v[244:245], off
	s_barrier
	s_waitcnt lgkmcnt(0)
	v_mfma_f32_16x16x32_bf16 v[92:95], v[186:189], v[218:221], v[92:95]
	v_mfma_f32_16x16x32_bf16 v[88:91], v[186:189], v[230:233], v[88:91]
	v_mfma_f32_16x16x32_bf16 v[84:87], v[194:197], v[218:221], v[84:87]
	v_mfma_f32_16x16x32_bf16 v[80:83], v[194:197], v[230:233], v[80:83]
	v_mfma_f32_16x16x32_bf16 v[76:79], v[202:205], v[218:221], v[76:79]
	v_mfma_f32_16x16x32_bf16 v[72:75], v[202:205], v[230:233], v[72:75]
	v_mfma_f32_16x16x32_bf16 v[68:71], v[210:213], v[218:221], v[68:71]
	v_mfma_f32_16x16x32_bf16 v[64:67], v[210:213], v[230:233], v[64:67]
	v_mfma_f32_16x16x32_bf16 v[92:95], v[190:193], v[226:229], v[92:95]
	v_mfma_f32_16x16x32_bf16 v[88:91], v[190:193], v[234:237], v[88:91]
	v_mfma_f32_16x16x32_bf16 v[84:87], v[198:201], v[226:229], v[84:87]
	v_mfma_f32_16x16x32_bf16 v[80:83], v[198:201], v[234:237], v[80:83]
	v_mfma_f32_16x16x32_bf16 v[76:79], v[206:209], v[226:229], v[76:79]
	v_mfma_f32_16x16x32_bf16 v[72:75], v[206:209], v[234:237], v[72:75]
	v_mfma_f32_16x16x32_bf16 v[68:71], v[214:217], v[226:229], v[68:71]
	v_mfma_f32_16x16x32_bf16 v[64:67], v[214:217], v[234:237], v[64:67]
	v_readfirstlane_b32 s19, v150
	v_lshl_add_u64 v[244:245], v[222:223], 0, s[14:15]
	s_mov_b32 m0, s19
	v_readfirstlane_b32 s19, v151
	s_barrier
	ds_read_b128 v[186:189], v163 offset:16384
	ds_read_b128 v[190:193], v163 offset:17408
	ds_read_b128 v[194:197], v129 offset:16384
	ds_read_b128 v[198:201], v129 offset:17408
	ds_read_b128 v[202:205], v131 offset:16384
	ds_read_b128 v[206:209], v131 offset:17408
	ds_read_b128 v[210:213], v132 offset:16384
	ds_read_b128 v[214:217], v132 offset:17408
	global_load_lds_dwordx4 v[244:245], off
	v_lshl_add_u64 v[244:245], v[238:239], 0, s[14:15]
	s_mov_b32 m0, s19
	s_nop 0
	global_load_lds_dwordx4 v[244:245], off
	s_barrier
	s_waitcnt lgkmcnt(0)
	v_mfma_f32_16x16x32_bf16 v[60:63], v[186:189], v[170:173], v[60:63]
	v_mfma_f32_16x16x32_bf16 v[56:59], v[186:189], v[178:181], v[56:59]
	v_mfma_f32_16x16x32_bf16 v[52:55], v[194:197], v[170:173], v[52:55]
	v_mfma_f32_16x16x32_bf16 v[48:51], v[194:197], v[178:181], v[48:51]
	v_mfma_f32_16x16x32_bf16 v[44:47], v[202:205], v[170:173], v[44:47]
	v_mfma_f32_16x16x32_bf16 v[40:43], v[202:205], v[178:181], v[40:43]
	v_mfma_f32_16x16x32_bf16 v[36:39], v[210:213], v[170:173], v[36:39]
	v_mfma_f32_16x16x32_bf16 v[32:35], v[210:213], v[178:181], v[32:35]
	v_mfma_f32_16x16x32_bf16 v[60:63], v[190:193], v[174:177], v[60:63]
	v_mfma_f32_16x16x32_bf16 v[56:59], v[190:193], v[182:185], v[56:59]
	v_mfma_f32_16x16x32_bf16 v[52:55], v[198:201], v[174:177], v[52:55]
	v_mfma_f32_16x16x32_bf16 v[48:51], v[198:201], v[182:185], v[48:51]
	v_mfma_f32_16x16x32_bf16 v[44:47], v[206:209], v[174:177], v[44:47]
	v_mfma_f32_16x16x32_bf16 v[40:43], v[206:209], v[182:185], v[40:43]
	v_mfma_f32_16x16x32_bf16 v[36:39], v[214:217], v[174:177], v[36:39]
	v_mfma_f32_16x16x32_bf16 v[32:35], v[214:217], v[182:185], v[32:35]
	s_barrier
	v_readfirstlane_b32 s19, v152
	v_lshl_add_u64 v[170:171], v[240:241], 0, s[16:17]
	s_mov_b32 m0, s19
	v_readfirstlane_b32 s19, v153
	global_load_lds_dwordx4 v[170:171], off
	v_lshl_add_u64 v[170:171], v[242:243], 0, s[16:17]
	s_mov_b32 m0, s19
	s_nop 0
	global_load_lds_dwordx4 v[170:171], off
	s_waitcnt vmcnt(6)
	s_barrier
	v_mfma_f32_16x16x32_bf16 v[28:31], v[186:189], v[218:221], v[28:31]
	v_mfma_f32_16x16x32_bf16 v[24:27], v[186:189], v[230:233], v[24:27]
	v_mfma_f32_16x16x32_bf16 v[20:23], v[194:197], v[218:221], v[20:23]
	v_mfma_f32_16x16x32_bf16 v[16:19], v[194:197], v[230:233], v[16:19]
	v_mfma_f32_16x16x32_bf16 v[12:15], v[202:205], v[218:221], v[12:15]
	v_mfma_f32_16x16x32_bf16 v[8:11], v[202:205], v[230:233], v[8:11]
	v_mfma_f32_16x16x32_bf16 v[4:7], v[210:213], v[218:221], v[4:7]
	v_mfma_f32_16x16x32_bf16 v[0:3], v[210:213], v[230:233], v[0:3]
	v_mfma_f32_16x16x32_bf16 v[28:31], v[190:193], v[226:229], v[28:31]
	v_mfma_f32_16x16x32_bf16 v[24:27], v[190:193], v[234:237], v[24:27]
	v_mfma_f32_16x16x32_bf16 v[20:23], v[198:201], v[226:229], v[20:23]
	v_mfma_f32_16x16x32_bf16 v[16:19], v[198:201], v[234:237], v[16:19]
	v_mfma_f32_16x16x32_bf16 v[12:15], v[206:209], v[226:229], v[12:15]
	v_mfma_f32_16x16x32_bf16 v[8:11], v[206:209], v[234:237], v[8:11]
	v_mfma_f32_16x16x32_bf16 v[4:7], v[214:217], v[226:229], v[4:7]
	v_mfma_f32_16x16x32_bf16 v[0:3], v[214:217], v[234:237], v[0:3]
	s_barrier
	ds_read_b128 v[170:173], v165
	ds_read_b128 v[174:177], v165 offset:1024
	ds_read_b128 v[178:181], v165 offset:2048
	ds_read_b128 v[182:185], v165 offset:3072
	v_readfirstlane_b32 s19, v154
	v_lshl_add_u64 v[218:219], v[222:223], 0, s[34:35]
	s_mov_b32 m0, s19
	v_readfirstlane_b32 s19, v155
	ds_read_b128 v[186:189], v163 offset:32768
	ds_read_b128 v[190:193], v163 offset:33792
	ds_read_b128 v[194:197], v129 offset:32768
	ds_read_b128 v[198:201], v129 offset:33792
	ds_read_b128 v[202:205], v131 offset:32768
	ds_read_b128 v[206:209], v131 offset:33792
	ds_read_b128 v[210:213], v132 offset:32768
	ds_read_b128 v[214:217], v132 offset:33792
	global_load_lds_dwordx4 v[218:219], off
	v_lshl_add_u64 v[218:219], v[238:239], 0, s[34:35]
	s_mov_b32 m0, s19
	s_nop 0
	global_load_lds_dwordx4 v[218:219], off
	s_waitcnt lgkmcnt(8)
	s_barrier
	s_waitcnt lgkmcnt(0)
	v_mfma_f32_16x16x32_bf16 v[124:127], v[186:189], v[170:173], v[124:127]
	v_mfma_f32_16x16x32_bf16 v[120:123], v[186:189], v[178:181], v[120:123]
	v_mfma_f32_16x16x32_bf16 v[116:119], v[194:197], v[170:173], v[116:119]
	v_mfma_f32_16x16x32_bf16 v[112:115], v[194:197], v[178:181], v[112:115]
	v_mfma_f32_16x16x32_bf16 v[108:111], v[202:205], v[170:173], v[108:111]
	v_mfma_f32_16x16x32_bf16 v[104:107], v[202:205], v[178:181], v[104:107]
	v_mfma_f32_16x16x32_bf16 v[100:103], v[210:213], v[170:173], v[100:103]
	v_mfma_f32_16x16x32_bf16 v[96:99], v[210:213], v[178:181], v[96:99]
	v_mfma_f32_16x16x32_bf16 v[124:127], v[190:193], v[174:177], v[124:127]
	v_mfma_f32_16x16x32_bf16 v[120:123], v[190:193], v[182:185], v[120:123]
	v_mfma_f32_16x16x32_bf16 v[116:119], v[198:201], v[174:177], v[116:119]
	v_mfma_f32_16x16x32_bf16 v[112:115], v[198:201], v[182:185], v[112:115]
	v_mfma_f32_16x16x32_bf16 v[108:111], v[206:209], v[174:177], v[108:111]
	v_mfma_f32_16x16x32_bf16 v[104:107], v[206:209], v[182:185], v[104:107]
	v_mfma_f32_16x16x32_bf16 v[100:103], v[214:217], v[174:177], v[100:103]
	v_mfma_f32_16x16x32_bf16 v[96:99], v[214:217], v[182:185], v[96:99]
	s_barrier
	v_readfirstlane_b32 s19, v156
	v_lshl_add_u64 v[244:245], v[240:241], 0, s[36:37]
	s_mov_b32 m0, s19
	v_readfirstlane_b32 s19, v157
	ds_read_b128 v[218:221], v166
	ds_read_b128 v[226:229], v166 offset:1024
	ds_read_b128 v[230:233], v166 offset:2048
	ds_read_b128 v[234:237], v166 offset:3072
	global_load_lds_dwordx4 v[244:245], off
	v_lshl_add_u64 v[244:245], v[242:243], 0, s[36:37]
	s_mov_b32 m0, s19
	s_nop 0
	global_load_lds_dwordx4 v[244:245], off
	s_barrier
	s_waitcnt lgkmcnt(0)
	v_mfma_f32_16x16x32_bf16 v[92:95], v[186:189], v[218:221], v[92:95]
	v_mfma_f32_16x16x32_bf16 v[88:91], v[186:189], v[230:233], v[88:91]
	v_mfma_f32_16x16x32_bf16 v[84:87], v[194:197], v[218:221], v[84:87]
	v_mfma_f32_16x16x32_bf16 v[80:83], v[194:197], v[230:233], v[80:83]
	v_mfma_f32_16x16x32_bf16 v[76:79], v[202:205], v[218:221], v[76:79]
	v_mfma_f32_16x16x32_bf16 v[72:75], v[202:205], v[230:233], v[72:75]
	v_mfma_f32_16x16x32_bf16 v[68:71], v[210:213], v[218:221], v[68:71]
	v_mfma_f32_16x16x32_bf16 v[64:67], v[210:213], v[230:233], v[64:67]
	v_mfma_f32_16x16x32_bf16 v[92:95], v[190:193], v[226:229], v[92:95]
	v_mfma_f32_16x16x32_bf16 v[88:91], v[190:193], v[234:237], v[88:91]
	v_mfma_f32_16x16x32_bf16 v[84:87], v[198:201], v[226:229], v[84:87]
	v_mfma_f32_16x16x32_bf16 v[80:83], v[198:201], v[234:237], v[80:83]
	v_mfma_f32_16x16x32_bf16 v[76:79], v[206:209], v[226:229], v[76:79]
	v_mfma_f32_16x16x32_bf16 v[72:75], v[206:209], v[234:237], v[72:75]
	v_mfma_f32_16x16x32_bf16 v[68:71], v[214:217], v[226:229], v[68:71]
	v_mfma_f32_16x16x32_bf16 v[64:67], v[214:217], v[234:237], v[64:67]
	v_readfirstlane_b32 s19, v158
	v_lshl_add_u64 v[222:223], v[222:223], 0, s[38:39]
	s_mov_b32 m0, s19
	v_readfirstlane_b32 s19, v159
	s_barrier
	ds_read_b128 v[186:189], v163 offset:49152
	ds_read_b128 v[190:193], v163 offset:50176
	ds_read_b128 v[194:197], v129 offset:49152
	ds_read_b128 v[198:201], v129 offset:50176
	ds_read_b128 v[202:205], v131 offset:49152
	ds_read_b128 v[206:209], v131 offset:50176
	ds_read_b128 v[210:213], v132 offset:49152
	ds_read_b128 v[214:217], v132 offset:50176
	global_load_lds_dwordx4 v[222:223], off
	v_lshl_add_u64 v[222:223], v[238:239], 0, s[38:39]
	s_mov_b32 m0, s19
	s_nop 0
	global_load_lds_dwordx4 v[222:223], off
	s_barrier
	s_waitcnt lgkmcnt(0)
	v_mfma_f32_16x16x32_bf16 v[60:63], v[186:189], v[170:173], v[60:63]
	v_mfma_f32_16x16x32_bf16 v[56:59], v[186:189], v[178:181], v[56:59]
	v_mfma_f32_16x16x32_bf16 v[52:55], v[194:197], v[170:173], v[52:55]
	v_mfma_f32_16x16x32_bf16 v[48:51], v[194:197], v[178:181], v[48:51]
	v_mfma_f32_16x16x32_bf16 v[44:47], v[202:205], v[170:173], v[44:47]
	v_mfma_f32_16x16x32_bf16 v[40:43], v[202:205], v[178:181], v[40:43]
	v_mfma_f32_16x16x32_bf16 v[36:39], v[210:213], v[170:173], v[36:39]
	v_mfma_f32_16x16x32_bf16 v[32:35], v[210:213], v[178:181], v[32:35]
	v_mfma_f32_16x16x32_bf16 v[60:63], v[190:193], v[174:177], v[60:63]
	v_mfma_f32_16x16x32_bf16 v[56:59], v[190:193], v[182:185], v[56:59]
	v_mfma_f32_16x16x32_bf16 v[52:55], v[198:201], v[174:177], v[52:55]
	v_mfma_f32_16x16x32_bf16 v[48:51], v[198:201], v[182:185], v[48:51]
	v_mfma_f32_16x16x32_bf16 v[44:47], v[206:209], v[174:177], v[44:47]
	v_mfma_f32_16x16x32_bf16 v[40:43], v[206:209], v[182:185], v[40:43]
	v_mfma_f32_16x16x32_bf16 v[36:39], v[214:217], v[174:177], v[36:39]
	v_mfma_f32_16x16x32_bf16 v[32:35], v[214:217], v[182:185], v[32:35]
	s_barrier
	v_readfirstlane_b32 s19, v160
	v_lshl_add_u64 v[170:171], v[240:241], 0, s[40:41]
	s_mov_b32 m0, s19
	v_readfirstlane_b32 s19, v161
	global_load_lds_dwordx4 v[170:171], off
	v_lshl_add_u64 v[170:171], v[242:243], 0, s[40:41]
	s_mov_b32 m0, s19
	s_nop 0
	global_load_lds_dwordx4 v[170:171], off
	s_waitcnt vmcnt(6)
	s_barrier
	v_mfma_f32_16x16x32_bf16 v[28:31], v[186:189], v[218:221], v[28:31]
	v_mfma_f32_16x16x32_bf16 v[24:27], v[186:189], v[230:233], v[24:27]
	v_mfma_f32_16x16x32_bf16 v[20:23], v[194:197], v[218:221], v[20:23]
	v_mfma_f32_16x16x32_bf16 v[16:19], v[194:197], v[230:233], v[16:19]
	v_mfma_f32_16x16x32_bf16 v[12:15], v[202:205], v[218:221], v[12:15]
	v_mfma_f32_16x16x32_bf16 v[8:11], v[202:205], v[230:233], v[8:11]
	v_mfma_f32_16x16x32_bf16 v[4:7], v[210:213], v[218:221], v[4:7]
	v_mfma_f32_16x16x32_bf16 v[0:3], v[210:213], v[230:233], v[0:3]
	v_mfma_f32_16x16x32_bf16 v[28:31], v[190:193], v[226:229], v[28:31]
	v_mfma_f32_16x16x32_bf16 v[24:27], v[190:193], v[234:237], v[24:27]
	v_mfma_f32_16x16x32_bf16 v[20:23], v[198:201], v[226:229], v[20:23]
	v_mfma_f32_16x16x32_bf16 v[16:19], v[198:201], v[234:237], v[16:19]
	v_mfma_f32_16x16x32_bf16 v[12:15], v[206:209], v[226:229], v[12:15]
	v_mfma_f32_16x16x32_bf16 v[8:11], v[206:209], v[234:237], v[8:11]
	v_mfma_f32_16x16x32_bf16 v[4:7], v[214:217], v[226:229], v[4:7]
	v_mfma_f32_16x16x32_bf16 v[0:3], v[214:217], v[234:237], v[0:3]
	s_add_i32 s18, s18, 2
	s_add_u32 s22, s22, 0x100
	s_addc_u32 s23, s23, 0
	s_cmp_lt_u32 s18, 28
	s_barrier
	s_cbranch_scc1 .LBB0_921
	v_readfirstlane_b32 s18, v167
	v_lshl_add_u64 v[136:137], v[136:137], 0, s[44:45]
	s_mov_b32 m0, s18
	v_readfirstlane_b32 s18, v168
	ds_read_b128 v[138:141], v162
	ds_read_b128 v[142:145], v162 offset:1024
	ds_read_b128 v[170:173], v162 offset:2048
	ds_read_b128 v[174:177], v162 offset:3072
	ds_read_b128 v[178:181], v163
	ds_read_b128 v[182:185], v163 offset:1024
	ds_read_b128 v[186:189], v129
	ds_read_b128 v[190:193], v129 offset:1024
	ds_read_b128 v[194:197], v131
	ds_read_b128 v[198:201], v131 offset:1024
	ds_read_b128 v[202:205], v132
	ds_read_b128 v[206:209], v132 offset:1024
	global_load_lds_dwordx4 v[136:137], off
	v_lshl_add_u64 v[134:135], v[134:135], 0, s[44:45]
	s_mov_b32 m0, s18
	s_nop 0
	global_load_lds_dwordx4 v[134:135], off
	s_barrier
	s_waitcnt lgkmcnt(0)
	v_mfma_f32_16x16x32_bf16 v[124:127], v[178:181], v[138:141], v[124:127]
	v_mfma_f32_16x16x32_bf16 v[120:123], v[178:181], v[170:173], v[120:123]
	v_mfma_f32_16x16x32_bf16 v[116:119], v[186:189], v[138:141], v[116:119]
	v_mfma_f32_16x16x32_bf16 v[112:115], v[186:189], v[170:173], v[112:115]
	v_mfma_f32_16x16x32_bf16 v[124:127], v[182:185], v[142:145], v[124:127]
	v_mfma_f32_16x16x32_bf16 v[120:123], v[182:185], v[174:177], v[120:123]
	v_mfma_f32_16x16x32_bf16 v[116:119], v[190:193], v[142:145], v[116:119]
	v_mfma_f32_16x16x32_bf16 v[112:115], v[190:193], v[174:177], v[112:115]
	v_mfma_f32_16x16x32_bf16 v[108:111], v[194:197], v[138:141], v[108:111]
	v_mfma_f32_16x16x32_bf16 v[104:107], v[194:197], v[170:173], v[104:107]
	v_mfma_f32_16x16x32_bf16 v[100:103], v[202:205], v[138:141], v[100:103]
	v_mfma_f32_16x16x32_bf16 v[96:99], v[202:205], v[170:173], v[96:99]
	v_mfma_f32_16x16x32_bf16 v[134:137], v[198:201], v[142:145], v[108:111]
	v_mfma_f32_16x16x32_bf16 v[210:213], v[198:201], v[174:177], v[104:107]
	v_mfma_f32_16x16x32_bf16 v[214:217], v[206:209], v[142:145], v[100:103]
	v_mfma_f32_16x16x32_bf16 v[218:221], v[206:209], v[174:177], v[96:99]
	s_barrier
	s_nop 1
	ds_read_b128 v[96:99], v164
	ds_read_b128 v[100:103], v164 offset:1024
	ds_read_b128 v[104:107], v164 offset:2048
	ds_read_b128 v[108:111], v164 offset:3072
	s_barrier
	s_waitcnt lgkmcnt(0)
	v_mfma_f32_16x16x32_bf16 v[92:95], v[178:181], v[96:99], v[92:95]
	v_mfma_f32_16x16x32_bf16 v[88:91], v[178:181], v[104:107], v[88:91]
	v_mfma_f32_16x16x32_bf16 v[84:87], v[186:189], v[96:99], v[84:87]
	v_mfma_f32_16x16x32_bf16 v[80:83], v[186:189], v[104:107], v[80:83]
	v_mfma_f32_16x16x32_bf16 v[92:95], v[182:185], v[100:103], v[92:95]
	v_mfma_f32_16x16x32_bf16 v[88:91], v[182:185], v[108:111], v[88:91]
	v_mfma_f32_16x16x32_bf16 v[84:87], v[190:193], v[100:103], v[84:87]
	v_mfma_f32_16x16x32_bf16 v[80:83], v[190:193], v[108:111], v[80:83]
	v_mfma_f32_16x16x32_bf16 v[76:79], v[194:197], v[96:99], v[76:79]
	v_mfma_f32_16x16x32_bf16 v[72:75], v[194:197], v[104:107], v[72:75]
	v_mfma_f32_16x16x32_bf16 v[68:71], v[202:205], v[96:99], v[68:71]
	v_mfma_f32_16x16x32_bf16 v[64:67], v[202:205], v[104:107], v[64:67]
	v_mfma_f32_16x16x32_bf16 v[178:181], v[198:201], v[100:103], v[76:79]
	v_mfma_f32_16x16x32_bf16 v[182:185], v[198:201], v[108:111], v[72:75]
	v_mfma_f32_16x16x32_bf16 v[186:189], v[206:209], v[100:103], v[68:71]
	v_mfma_f32_16x16x32_bf16 v[190:193], v[206:209], v[108:111], v[64:67]
	s_barrier
	s_nop 1
	ds_read_b128 v[64:67], v163 offset:16384
	ds_read_b128 v[68:71], v163 offset:17408
	ds_read_b128 v[72:75], v129 offset:16384
	ds_read_b128 v[76:79], v129 offset:17408
	ds_read_b128 v[194:197], v131 offset:16384
	ds_read_b128 v[198:201], v131 offset:17408
	ds_read_b128 v[202:205], v132 offset:16384
	ds_read_b128 v[206:209], v132 offset:17408
	s_waitcnt vmcnt(4)
	s_barrier
	s_waitcnt lgkmcnt(0)
	v_mfma_f32_16x16x32_bf16 v[60:63], v[64:67], v[138:141], v[60:63]
	v_mfma_f32_16x16x32_bf16 v[56:59], v[64:67], v[170:173], v[56:59]
	v_mfma_f32_16x16x32_bf16 v[52:55], v[72:75], v[138:141], v[52:55]
	v_mfma_f32_16x16x32_bf16 v[48:51], v[72:75], v[170:173], v[48:51]
	v_mfma_f32_16x16x32_bf16 v[60:63], v[68:71], v[142:145], v[60:63]
	v_mfma_f32_16x16x32_bf16 v[56:59], v[68:71], v[174:177], v[56:59]
	v_mfma_f32_16x16x32_bf16 v[52:55], v[76:79], v[142:145], v[52:55]
	v_mfma_f32_16x16x32_bf16 v[48:51], v[76:79], v[174:177], v[48:51]
	v_mfma_f32_16x16x32_bf16 v[44:47], v[194:197], v[138:141], v[44:47]
	v_mfma_f32_16x16x32_bf16 v[40:43], v[194:197], v[170:173], v[40:43]
	v_mfma_f32_16x16x32_bf16 v[36:39], v[202:205], v[138:141], v[36:39]
	v_mfma_f32_16x16x32_bf16 v[32:35], v[202:205], v[170:173], v[32:35]
	v_mfma_f32_16x16x32_bf16 v[226:229], v[198:201], v[142:145], v[44:47]
	v_mfma_f32_16x16x32_bf16 v[230:233], v[198:201], v[174:177], v[40:43]
	v_mfma_f32_16x16x32_bf16 v[138:141], v[206:209], v[142:145], v[36:39]
	v_mfma_f32_16x16x32_bf16 v[142:145], v[206:209], v[174:177], v[32:35]
	v_mfma_f32_16x16x32_bf16 v[28:31], v[64:67], v[96:99], v[28:31]
	v_mfma_f32_16x16x32_bf16 v[24:27], v[64:67], v[104:107], v[24:27]
	v_mfma_f32_16x16x32_bf16 v[20:23], v[72:75], v[96:99], v[20:23]
	v_mfma_f32_16x16x32_bf16 v[16:19], v[72:75], v[104:107], v[16:19]
	v_mfma_f32_16x16x32_bf16 v[28:31], v[68:71], v[100:103], v[28:31]
	v_mfma_f32_16x16x32_bf16 v[24:27], v[68:71], v[108:111], v[24:27]
	v_mfma_f32_16x16x32_bf16 v[20:23], v[76:79], v[100:103], v[20:23]
	v_mfma_f32_16x16x32_bf16 v[16:19], v[76:79], v[108:111], v[16:19]
	v_mfma_f32_16x16x32_bf16 v[12:15], v[194:197], v[96:99], v[12:15]
	v_mfma_f32_16x16x32_bf16 v[8:11], v[194:197], v[104:107], v[8:11]
	v_mfma_f32_16x16x32_bf16 v[4:7], v[202:205], v[96:99], v[4:7]
	v_mfma_f32_16x16x32_bf16 v[0:3], v[202:205], v[104:107], v[0:3]
	v_mfma_f32_16x16x32_bf16 v[168:171], v[198:201], v[100:103], v[12:15]
	v_mfma_f32_16x16x32_bf16 v[172:175], v[198:201], v[108:111], v[8:11]
	v_mfma_f32_16x16x32_bf16 v[194:197], v[206:209], v[100:103], v[4:7]
	v_mfma_f32_16x16x32_bf16 v[198:201], v[206:209], v[108:111], v[0:3]
	s_barrier
	s_nop 1
	ds_read_b128 v[0:3], v165
	ds_read_b128 v[4:7], v165 offset:1024
	ds_read_b128 v[202:205], v165 offset:2048
	ds_read_b128 v[206:209], v165 offset:3072
	ds_read_b128 v[8:11], v163 offset:32768
	ds_read_b128 v[12:15], v163 offset:33792
	ds_read_b128 v[32:35], v129 offset:32768
	ds_read_b128 v[36:39], v129 offset:33792
	ds_read_b128 v[40:43], v131 offset:32768
	ds_read_b128 v[44:47], v131 offset:33792
	ds_read_b128 v[234:237], v132 offset:32768
	ds_read_b128 v[238:241], v132 offset:33792
	s_waitcnt vmcnt(2)
	s_barrier
	s_waitcnt lgkmcnt(0)
	v_mfma_f32_16x16x32_bf16 v[64:67], v[8:11], v[0:3], v[124:127]
	v_mfma_f32_16x16x32_bf16 v[104:107], v[12:15], v[4:7], v[64:67]
	v_mfma_f32_16x16x32_bf16 v[64:67], v[8:11], v[202:205], v[120:123]
	v_mfma_f32_16x16x32_bf16 v[108:111], v[12:15], v[206:209], v[64:67]
	v_mfma_f32_16x16x32_bf16 v[64:67], v[32:35], v[0:3], v[116:119]
	v_mfma_f32_16x16x32_bf16 v[96:99], v[36:39], v[4:7], v[64:67]
	v_mfma_f32_16x16x32_bf16 v[64:67], v[32:35], v[202:205], v[112:115]
	v_mfma_f32_16x16x32_bf16 v[100:103], v[36:39], v[206:209], v[64:67]
	v_mfma_f32_16x16x32_bf16 v[64:67], v[40:43], v[0:3], v[134:137]
	v_mfma_f32_16x16x32_bf16 v[72:75], v[44:47], v[4:7], v[64:67]
	v_mfma_f32_16x16x32_bf16 v[64:67], v[40:43], v[202:205], v[210:213]
	v_mfma_f32_16x16x32_bf16 v[76:79], v[44:47], v[206:209], v[64:67]
	v_mfma_f32_16x16x32_bf16 v[64:67], v[234:237], v[0:3], v[214:217]
	v_mfma_f32_16x16x32_bf16 v[68:71], v[234:237], v[202:205], v[218:221]
	v_mfma_f32_16x16x32_bf16 v[64:67], v[238:241], v[4:7], v[64:67]
	v_mfma_f32_16x16x32_bf16 v[68:71], v[238:241], v[206:209], v[68:71]
	s_barrier
	ds_read_b128 v[134:137], v166
	ds_read_b128 v[210:213], v166 offset:1024
	ds_read_b128 v[214:217], v166 offset:2048
	ds_read_b128 v[218:221], v166 offset:3072
	s_waitcnt vmcnt(0)
	s_barrier
	s_waitcnt lgkmcnt(0)
	v_mfma_f32_16x16x32_bf16 v[92:95], v[8:11], v[134:137], v[92:95]
	v_mfma_f32_16x16x32_bf16 v[8:11], v[8:11], v[214:217], v[88:91]
	v_mfma_f32_16x16x32_bf16 v[124:127], v[12:15], v[218:221], v[8:11]
	v_mfma_f32_16x16x32_bf16 v[8:11], v[32:35], v[134:137], v[84:87]
	v_mfma_f32_16x16x32_bf16 v[112:115], v[36:39], v[210:213], v[8:11]
	v_mfma_f32_16x16x32_bf16 v[8:11], v[32:35], v[214:217], v[80:83]
	v_mfma_f32_16x16x32_bf16 v[116:119], v[36:39], v[218:221], v[8:11]
	v_mfma_f32_16x16x32_bf16 v[8:11], v[40:43], v[134:137], v[178:181]
	v_mfma_f32_16x16x32_bf16 v[88:91], v[44:47], v[210:213], v[8:11]
	v_mfma_f32_16x16x32_bf16 v[8:11], v[40:43], v[214:217], v[182:185]
	v_mfma_f32_16x16x32_bf16 v[120:123], v[12:15], v[210:213], v[92:95]
	v_mfma_f32_16x16x32_bf16 v[92:95], v[44:47], v[218:221], v[8:11]
	v_mfma_f32_16x16x32_bf16 v[8:11], v[234:237], v[134:137], v[186:189]
	v_mfma_f32_16x16x32_bf16 v[80:83], v[238:241], v[210:213], v[8:11]
	v_mfma_f32_16x16x32_bf16 v[8:11], v[234:237], v[214:217], v[190:193]
	v_mfma_f32_16x16x32_bf16 v[84:87], v[238:241], v[218:221], v[8:11]
	s_barrier
	ds_read_b128 v[176:179], v163 offset:49152
	ds_read_b128 v[180:183], v163 offset:50176
	ds_read_b128 v[184:187], v129 offset:49152
	ds_read_b128 v[188:191], v129 offset:50176
	ds_read_b128 v[234:237], v131 offset:49152
	ds_read_b128 v[238:241], v131 offset:50176
	ds_read_b128 v[242:245], v132 offset:49152
	ds_read_b128 v[246:249], v132 offset:50176
	s_barrier
	s_waitcnt lgkmcnt(0)
	v_mfma_f32_16x16x32_bf16 v[8:11], v[176:179], v[0:3], v[60:63]
	v_mfma_f32_16x16x32_bf16 v[40:43], v[180:183], v[4:7], v[8:11]
	v_mfma_f32_16x16x32_bf16 v[8:11], v[176:179], v[202:205], v[56:59]
	v_mfma_f32_16x16x32_bf16 v[44:47], v[180:183], v[206:209], v[8:11]
	v_mfma_f32_16x16x32_bf16 v[8:11], v[184:187], v[0:3], v[52:55]
	v_mfma_f32_16x16x32_bf16 v[32:35], v[188:191], v[4:7], v[8:11]
	v_mfma_f32_16x16x32_bf16 v[8:11], v[184:187], v[202:205], v[48:51]
	v_mfma_f32_16x16x32_bf16 v[36:39], v[188:191], v[206:209], v[8:11]
	v_mfma_f32_16x16x32_bf16 v[8:11], v[234:237], v[0:3], v[226:229]
	v_mfma_f32_16x16x32_bf16 v[0:3], v[242:245], v[0:3], v[138:141]
	v_mfma_f32_16x16x32_bf16 v[8:11], v[238:241], v[4:7], v[8:11]
	v_mfma_f32_16x16x32_bf16 v[12:15], v[234:237], v[202:205], v[230:233]
	v_mfma_f32_16x16x32_bf16 v[0:3], v[246:249], v[4:7], v[0:3]
	v_mfma_f32_16x16x32_bf16 v[4:7], v[242:245], v[202:205], v[142:145]
	v_mfma_f32_16x16x32_bf16 v[12:15], v[238:241], v[206:209], v[12:15]
	v_mfma_f32_16x16x32_bf16 v[4:7], v[246:249], v[206:209], v[4:7]
	v_mfma_f32_16x16x32_bf16 v[16:19], v[184:187], v[214:217], v[16:19]
	v_mfma_f32_16x16x32_bf16 v[24:27], v[176:179], v[214:217], v[24:27]
	v_mfma_f32_16x16x32_bf16 v[52:55], v[188:191], v[218:221], v[16:19]
	v_mfma_f32_16x16x32_bf16 v[16:19], v[234:237], v[134:137], v[168:171]
	v_mfma_f32_16x16x32_bf16 v[28:31], v[176:179], v[134:137], v[28:31]
	v_mfma_f32_16x16x32_bf16 v[60:63], v[180:183], v[218:221], v[24:27]
	v_mfma_f32_16x16x32_bf16 v[20:23], v[184:187], v[134:137], v[20:23]
	v_mfma_f32_16x16x32_bf16 v[24:27], v[238:241], v[210:213], v[16:19]
	v_mfma_f32_16x16x32_bf16 v[16:19], v[234:237], v[214:217], v[172:175]
	v_mfma_f32_16x16x32_bf16 v[56:59], v[180:183], v[210:213], v[28:31]
	v_mfma_f32_16x16x32_bf16 v[48:51], v[188:191], v[210:213], v[20:23]
	v_mfma_f32_16x16x32_bf16 v[28:31], v[238:241], v[218:221], v[16:19]
	v_mfma_f32_16x16x32_bf16 v[16:19], v[242:245], v[134:137], v[194:197]
	v_mfma_f32_16x16x32_bf16 v[20:23], v[242:245], v[214:217], v[198:201]
	v_mfma_f32_16x16x32_bf16 v[16:19], v[246:249], v[210:213], v[16:19]
	v_mfma_f32_16x16x32_bf16 v[20:23], v[246:249], v[218:221], v[20:23]
	s_andn2_b64 vcc, exec, s[4:5]
	s_barrier
	s_cbranch_vccnz .LBB0_913
	s_barrier
	s_branch .LBB0_913

.LBB0_1124:
	ds_read_b128 v[176:179], v246
	ds_read_b128 v[180:183], v246 offset:1024
	ds_read_b128 v[184:187], v246 offset:2048
	ds_read_b128 v[188:191], v246 offset:3072
	v_add_u32_e32 v220, 0xc000, v231
	v_lshl_add_u64 v[212:213], s[22:23], 0, v[200:201]
	v_readfirstlane_b32 s4, v220
	v_add_u32_e32 v221, 0xe000, v231
	v_add_u32_e32 v227, s58, v230
	v_add_u32_e32 v251, s59, v230
	v_add_u32_e32 v252, s60, v230
	v_lshl_add_u64 v[160:161], v[212:213], 0, s[34:35]
	s_mov_b32 m0, s4
	v_lshl_add_u64 v[214:215], s[22:23], 0, v[202:203]
	v_readfirstlane_b32 s4, v221
	s_waitcnt lgkmcnt(0)
	ds_read_b128 v[128:131], v247
	ds_read_b128 v[136:139], v247 offset:1024
	ds_read_b128 v[132:135], v227
	ds_read_b128 v[144:147], v227 offset:1024
	ds_read_b128 v[140:143], v251
	ds_read_b128 v[152:155], v251 offset:1024
	ds_read_b128 v[148:151], v252
	ds_read_b128 v[156:159], v252 offset:1024
	global_load_lds_dwordx4 v[160:161], off
	v_lshl_add_u64 v[160:161], v[214:215], 0, s[34:35]
	s_mov_b32 m0, s4
	s_nop 0
	global_load_lds_dwordx4 v[160:161], off
	s_waitcnt lgkmcnt(8)
	s_barrier
	s_waitcnt lgkmcnt(0)
	v_mfma_f32_16x16x32_bf16 v[124:127], v[128:131], v[176:179], v[124:127]
	v_mfma_f32_16x16x32_bf16 v[120:123], v[128:131], v[184:187], v[120:123]
	v_mfma_f32_16x16x32_bf16 v[116:119], v[132:135], v[176:179], v[116:119]
	v_mfma_f32_16x16x32_bf16 v[112:115], v[132:135], v[184:187], v[112:115]
	v_mfma_f32_16x16x32_bf16 v[108:111], v[140:143], v[176:179], v[108:111]
	v_mfma_f32_16x16x32_bf16 v[104:107], v[140:143], v[184:187], v[104:107]
	v_mfma_f32_16x16x32_bf16 v[100:103], v[148:151], v[176:179], v[100:103]
	v_mfma_f32_16x16x32_bf16 v[96:99], v[148:151], v[184:187], v[96:99]
	v_mfma_f32_16x16x32_bf16 v[124:127], v[136:139], v[180:183], v[124:127]
	v_mfma_f32_16x16x32_bf16 v[120:123], v[136:139], v[188:191], v[120:123]
	v_mfma_f32_16x16x32_bf16 v[116:119], v[144:147], v[180:183], v[116:119]
	v_mfma_f32_16x16x32_bf16 v[112:115], v[144:147], v[188:191], v[112:115]
	v_mfma_f32_16x16x32_bf16 v[108:111], v[152:155], v[180:183], v[108:111]
	v_mfma_f32_16x16x32_bf16 v[104:107], v[152:155], v[188:191], v[104:107]
	v_mfma_f32_16x16x32_bf16 v[100:103], v[156:159], v[180:183], v[100:103]
	v_mfma_f32_16x16x32_bf16 v[96:99], v[156:159], v[188:191], v[96:99]
	s_barrier
	v_lshl_add_u64 v[204:205], s[22:23], 0, v[192:193]
	v_readfirstlane_b32 s4, v236
	v_lshl_add_u64 v[206:207], v[204:205], 0, s[36:37]
	s_mov_b32 m0, s4
	ds_read_b128 v[160:163], v248
	ds_read_b128 v[164:167], v248 offset:1024
	ds_read_b128 v[168:171], v248 offset:2048
	ds_read_b128 v[172:175], v248 offset:3072
	global_load_lds_dwordx4 v[206:207], off
	v_lshl_add_u64 v[206:207], s[22:23], 0, v[194:195]
	v_readfirstlane_b32 s4, v237
	v_lshl_add_u64 v[216:217], v[206:207], 0, s[36:37]
	s_mov_b32 m0, s4
	s_nop 0
	global_load_lds_dwordx4 v[216:217], off
	s_barrier
	s_waitcnt lgkmcnt(0)
	v_mfma_f32_16x16x32_bf16 v[92:95], v[128:131], v[160:163], v[92:95]
	v_mfma_f32_16x16x32_bf16 v[88:91], v[128:131], v[168:171], v[88:91]
	v_mfma_f32_16x16x32_bf16 v[84:87], v[132:135], v[160:163], v[84:87]
	v_mfma_f32_16x16x32_bf16 v[80:83], v[132:135], v[168:171], v[80:83]
	v_mfma_f32_16x16x32_bf16 v[76:79], v[140:143], v[160:163], v[76:79]
	v_mfma_f32_16x16x32_bf16 v[72:75], v[140:143], v[168:171], v[72:75]
	v_mfma_f32_16x16x32_bf16 v[68:71], v[148:151], v[160:163], v[68:71]
	v_mfma_f32_16x16x32_bf16 v[64:67], v[148:151], v[168:171], v[64:67]
	v_mfma_f32_16x16x32_bf16 v[92:95], v[136:139], v[164:167], v[92:95]
	v_mfma_f32_16x16x32_bf16 v[88:91], v[136:139], v[172:175], v[88:91]
	v_mfma_f32_16x16x32_bf16 v[84:87], v[144:147], v[164:167], v[84:87]
	v_mfma_f32_16x16x32_bf16 v[80:83], v[144:147], v[172:175], v[80:83]
	v_mfma_f32_16x16x32_bf16 v[76:79], v[152:155], v[164:167], v[76:79]
	v_mfma_f32_16x16x32_bf16 v[72:75], v[152:155], v[172:175], v[72:75]
	v_mfma_f32_16x16x32_bf16 v[68:71], v[156:159], v[164:167], v[68:71]
	v_mfma_f32_16x16x32_bf16 v[64:67], v[156:159], v[172:175], v[64:67]
	v_cndmask_b32_e64 v216, 0, 1, s[6:7]
	v_cmp_ne_u32_e64 s[4:5], 1, v216
	s_andn2_b64 vcc, exec, s[6:7]
	s_barrier
	s_cbranch_vccnz .LBB0_1126
	ds_read_b128 v[128:131], v247 offset:16384
	ds_read_b128 v[136:139], v247 offset:17408
	ds_read_b128 v[132:135], v227 offset:16384
	ds_read_b128 v[144:147], v227 offset:17408
	ds_read_b128 v[140:143], v251 offset:16384
	ds_read_b128 v[152:155], v251 offset:17408
	ds_read_b128 v[148:151], v252 offset:16384
	ds_read_b128 v[156:159], v252 offset:17408
.LBB0_1126:
	v_lshl_add_u64 v[216:217], s[22:23], 0, v[196:197]
	v_readfirstlane_b32 s19, v231
	v_lshl_add_u64 v[218:219], v[216:217], 0, s[38:39]
	s_mov_b32 m0, s19
	v_readfirstlane_b32 s19, v232
	global_load_lds_dwordx4 v[218:219], off
	v_lshl_add_u64 v[218:219], s[22:23], 0, v[198:199]
	v_lshl_add_u64 v[222:223], v[218:219], 0, s[38:39]
	s_mov_b32 m0, s19
	s_and_b64 vcc, exec, s[4:5]
	global_load_lds_dwordx4 v[222:223], off
	s_barrier
	s_waitcnt lgkmcnt(0)
	s_cbranch_vccnz .LBB0_1128
	s_waitcnt lgkmcnt(0)
	v_mfma_f32_16x16x32_bf16 v[60:63], v[128:131], v[176:179], v[60:63]
	v_mfma_f32_16x16x32_bf16 v[56:59], v[128:131], v[184:187], v[56:59]
	v_mfma_f32_16x16x32_bf16 v[52:55], v[132:135], v[176:179], v[52:55]
	v_mfma_f32_16x16x32_bf16 v[48:51], v[132:135], v[184:187], v[48:51]
	v_mfma_f32_16x16x32_bf16 v[36:39], v[140:143], v[176:179], v[36:39]
	v_mfma_f32_16x16x32_bf16 v[32:35], v[140:143], v[184:187], v[32:35]
	v_mfma_f32_16x16x32_bf16 v[20:23], v[148:151], v[176:179], v[20:23]
	v_mfma_f32_16x16x32_bf16 v[16:19], v[148:151], v[184:187], v[16:19]
	v_mfma_f32_16x16x32_bf16 v[60:63], v[136:139], v[180:183], v[60:63]
	v_mfma_f32_16x16x32_bf16 v[56:59], v[136:139], v[188:191], v[56:59]
	v_mfma_f32_16x16x32_bf16 v[52:55], v[144:147], v[180:183], v[52:55]
	v_mfma_f32_16x16x32_bf16 v[48:51], v[144:147], v[188:191], v[48:51]
	v_mfma_f32_16x16x32_bf16 v[36:39], v[152:155], v[180:183], v[36:39]
	v_mfma_f32_16x16x32_bf16 v[32:35], v[152:155], v[188:191], v[32:35]
	v_mfma_f32_16x16x32_bf16 v[20:23], v[156:159], v[180:183], v[20:23]
	v_mfma_f32_16x16x32_bf16 v[16:19], v[156:159], v[188:191], v[16:19]
.LBB0_1128:
	s_barrier
	v_readfirstlane_b32 s19, v238
	v_lshl_add_u64 v[176:177], v[204:205], 0, s[40:41]
	s_mov_b32 m0, s19
	v_readfirstlane_b32 s19, v239
	global_load_lds_dwordx4 v[176:177], off
	v_lshl_add_u64 v[176:177], v[206:207], 0, s[40:41]
	s_mov_b32 m0, s19
	s_and_b64 vcc, exec, s[4:5]
	global_load_lds_dwordx4 v[176:177], off
	s_waitcnt vmcnt(6)
	s_barrier
	s_cbranch_vccnz .LBB0_1130
	s_waitcnt lgkmcnt(0)
	v_mfma_f32_16x16x32_bf16 v[44:47], v[128:131], v[160:163], v[44:47]
	v_mfma_f32_16x16x32_bf16 v[40:43], v[128:131], v[168:171], v[40:43]
	v_mfma_f32_16x16x32_bf16 v[28:31], v[132:135], v[160:163], v[28:31]
	v_mfma_f32_16x16x32_bf16 v[24:27], v[132:135], v[168:171], v[24:27]
	v_mfma_f32_16x16x32_bf16 v[12:15], v[140:143], v[160:163], v[12:15]
	v_mfma_f32_16x16x32_bf16 v[8:11], v[140:143], v[168:171], v[8:11]
	v_mfma_f32_16x16x32_bf16 v[4:7], v[148:151], v[160:163], v[4:7]
	v_mfma_f32_16x16x32_bf16 v[0:3], v[148:151], v[168:171], v[0:3]
	v_mfma_f32_16x16x32_bf16 v[44:47], v[136:139], v[164:167], v[44:47]
	v_mfma_f32_16x16x32_bf16 v[40:43], v[136:139], v[172:175], v[40:43]
	v_mfma_f32_16x16x32_bf16 v[28:31], v[144:147], v[164:167], v[28:31]
	v_mfma_f32_16x16x32_bf16 v[24:27], v[144:147], v[172:175], v[24:27]
	v_mfma_f32_16x16x32_bf16 v[12:15], v[152:155], v[164:167], v[12:15]
	v_mfma_f32_16x16x32_bf16 v[8:11], v[152:155], v[172:175], v[8:11]
	v_mfma_f32_16x16x32_bf16 v[4:7], v[156:159], v[164:167], v[4:7]
	v_mfma_f32_16x16x32_bf16 v[0:3], v[156:159], v[172:175], v[0:3]
.LBB0_1130:
	s_barrier
	ds_read_b128 v[176:179], v249
	ds_read_b128 v[180:183], v249 offset:1024
	ds_read_b128 v[184:187], v249 offset:2048
	ds_read_b128 v[188:191], v249 offset:3072
	v_readfirstlane_b32 s19, v233
	v_lshl_add_u64 v[160:161], v[212:213], 0, s[38:39]
	s_mov_b32 m0, s19
	v_readfirstlane_b32 s19, v234
	s_waitcnt lgkmcnt(0)
	ds_read_b128 v[140:143], v247 offset:32768
	ds_read_b128 v[156:159], v247 offset:33792
	ds_read_b128 v[136:139], v227 offset:32768
	ds_read_b128 v[152:155], v227 offset:33792
	ds_read_b128 v[132:135], v251 offset:32768
	ds_read_b128 v[148:151], v251 offset:33792
	ds_read_b128 v[128:131], v252 offset:32768
	ds_read_b128 v[144:147], v252 offset:33792
	global_load_lds_dwordx4 v[160:161], off
	v_lshl_add_u64 v[160:161], v[214:215], 0, s[38:39]
	s_mov_b32 m0, s19
	s_nop 0
	global_load_lds_dwordx4 v[160:161], off
	s_waitcnt lgkmcnt(8)
	s_barrier
	s_waitcnt lgkmcnt(0)
	v_mfma_f32_16x16x32_bf16 v[124:127], v[140:143], v[176:179], v[124:127]
	v_mfma_f32_16x16x32_bf16 v[120:123], v[140:143], v[184:187], v[120:123]
	v_mfma_f32_16x16x32_bf16 v[116:119], v[136:139], v[176:179], v[116:119]
	v_mfma_f32_16x16x32_bf16 v[112:115], v[136:139], v[184:187], v[112:115]
	v_mfma_f32_16x16x32_bf16 v[108:111], v[132:135], v[176:179], v[108:111]
	v_mfma_f32_16x16x32_bf16 v[104:107], v[132:135], v[184:187], v[104:107]
	v_mfma_f32_16x16x32_bf16 v[100:103], v[128:131], v[176:179], v[100:103]
	v_mfma_f32_16x16x32_bf16 v[96:99], v[128:131], v[184:187], v[96:99]
	v_mfma_f32_16x16x32_bf16 v[124:127], v[156:159], v[180:183], v[124:127]
	v_mfma_f32_16x16x32_bf16 v[120:123], v[156:159], v[188:191], v[120:123]
	v_mfma_f32_16x16x32_bf16 v[116:119], v[152:155], v[180:183], v[116:119]
	v_mfma_f32_16x16x32_bf16 v[112:115], v[152:155], v[188:191], v[112:115]
	v_mfma_f32_16x16x32_bf16 v[108:111], v[148:151], v[180:183], v[108:111]
	v_mfma_f32_16x16x32_bf16 v[104:107], v[148:151], v[188:191], v[104:107]
	v_mfma_f32_16x16x32_bf16 v[100:103], v[144:147], v[180:183], v[100:103]
	v_mfma_f32_16x16x32_bf16 v[96:99], v[144:147], v[188:191], v[96:99]
	s_barrier
	v_readfirstlane_b32 s19, v240
	v_lshl_add_u64 v[212:213], v[204:205], 0, s[44:45]
	s_mov_b32 m0, s19
	v_readfirstlane_b32 s19, v241
	ds_read_b128 v[160:163], v250
	ds_read_b128 v[164:167], v250 offset:1024
	ds_read_b128 v[168:171], v250 offset:2048
	ds_read_b128 v[172:175], v250 offset:3072
	global_load_lds_dwordx4 v[212:213], off
	v_lshl_add_u64 v[212:213], v[206:207], 0, s[44:45]
	s_mov_b32 m0, s19
	s_nop 0
	global_load_lds_dwordx4 v[212:213], off
	s_barrier
	s_waitcnt lgkmcnt(0)
	v_mfma_f32_16x16x32_bf16 v[92:95], v[140:143], v[160:163], v[92:95]
	v_mfma_f32_16x16x32_bf16 v[88:91], v[140:143], v[168:171], v[88:91]
	v_mfma_f32_16x16x32_bf16 v[84:87], v[136:139], v[160:163], v[84:87]
	v_mfma_f32_16x16x32_bf16 v[80:83], v[136:139], v[168:171], v[80:83]
	v_mfma_f32_16x16x32_bf16 v[76:79], v[132:135], v[160:163], v[76:79]
	v_mfma_f32_16x16x32_bf16 v[72:75], v[132:135], v[168:171], v[72:75]
	v_mfma_f32_16x16x32_bf16 v[68:71], v[128:131], v[160:163], v[68:71]
	v_mfma_f32_16x16x32_bf16 v[64:67], v[128:131], v[168:171], v[64:67]
	v_mfma_f32_16x16x32_bf16 v[92:95], v[156:159], v[164:167], v[92:95]
	v_mfma_f32_16x16x32_bf16 v[88:91], v[156:159], v[172:175], v[88:91]
	v_mfma_f32_16x16x32_bf16 v[84:87], v[152:155], v[164:167], v[84:87]
	v_mfma_f32_16x16x32_bf16 v[80:83], v[152:155], v[172:175], v[80:83]
	v_mfma_f32_16x16x32_bf16 v[76:79], v[148:151], v[164:167], v[76:79]
	v_mfma_f32_16x16x32_bf16 v[72:75], v[148:151], v[172:175], v[72:75]
	v_mfma_f32_16x16x32_bf16 v[68:71], v[144:147], v[164:167], v[68:71]
	v_mfma_f32_16x16x32_bf16 v[64:67], v[144:147], v[172:175], v[64:67]
	s_and_b64 vcc, exec, s[4:5]
	s_barrier
	s_cbranch_vccnz .LBB0_1132
	ds_read_b128 v[140:143], v247 offset:49152
	ds_read_b128 v[156:159], v247 offset:50176
	ds_read_b128 v[136:139], v227 offset:49152
	ds_read_b128 v[152:155], v227 offset:50176
	ds_read_b128 v[132:135], v251 offset:49152
	ds_read_b128 v[148:151], v251 offset:50176
	ds_read_b128 v[128:131], v252 offset:49152
	ds_read_b128 v[144:147], v252 offset:50176
.LBB0_1132:
	v_readfirstlane_b32 s19, v242
	v_lshl_add_u64 v[212:213], v[216:217], 0, s[46:47]
	s_mov_b32 m0, s19
	v_readfirstlane_b32 s19, v243
	global_load_lds_dwordx4 v[212:213], off
	v_lshl_add_u64 v[212:213], v[218:219], 0, s[46:47]
	s_mov_b32 m0, s19
	s_and_b64 vcc, exec, s[4:5]
	global_load_lds_dwordx4 v[212:213], off
	s_barrier
	s_waitcnt lgkmcnt(0)
	s_cbranch_vccnz .LBB0_1134
	s_waitcnt lgkmcnt(0)
	v_mfma_f32_16x16x32_bf16 v[60:63], v[140:143], v[176:179], v[60:63]
	v_mfma_f32_16x16x32_bf16 v[56:59], v[140:143], v[184:187], v[56:59]
	v_mfma_f32_16x16x32_bf16 v[52:55], v[136:139], v[176:179], v[52:55]
	v_mfma_f32_16x16x32_bf16 v[48:51], v[136:139], v[184:187], v[48:51]
	v_mfma_f32_16x16x32_bf16 v[36:39], v[132:135], v[176:179], v[36:39]
	v_mfma_f32_16x16x32_bf16 v[32:35], v[132:135], v[184:187], v[32:35]
	v_mfma_f32_16x16x32_bf16 v[20:23], v[128:131], v[176:179], v[20:23]
	v_mfma_f32_16x16x32_bf16 v[16:19], v[128:131], v[184:187], v[16:19]
	v_mfma_f32_16x16x32_bf16 v[60:63], v[156:159], v[180:183], v[60:63]
	v_mfma_f32_16x16x32_bf16 v[56:59], v[156:159], v[188:191], v[56:59]
	v_mfma_f32_16x16x32_bf16 v[52:55], v[152:155], v[180:183], v[52:55]
	v_mfma_f32_16x16x32_bf16 v[48:51], v[152:155], v[188:191], v[48:51]
	v_mfma_f32_16x16x32_bf16 v[36:39], v[148:151], v[180:183], v[36:39]
	v_mfma_f32_16x16x32_bf16 v[32:35], v[148:151], v[188:191], v[32:35]
	v_mfma_f32_16x16x32_bf16 v[20:23], v[144:147], v[180:183], v[20:23]
	v_mfma_f32_16x16x32_bf16 v[16:19], v[144:147], v[188:191], v[16:19]
.LBB0_1134:
	s_barrier
	v_readfirstlane_b32 s19, v244
	v_lshl_add_u64 v[176:177], v[204:205], 0, s[48:49]
	s_mov_b32 m0, s19
	v_readfirstlane_b32 s19, v245
	global_load_lds_dwordx4 v[176:177], off
	v_lshl_add_u64 v[176:177], v[206:207], 0, s[48:49]
	s_mov_b32 m0, s19
	s_and_b64 vcc, exec, s[4:5]
	global_load_lds_dwordx4 v[176:177], off
	s_waitcnt vmcnt(6)
	s_barrier
	s_cbranch_vccnz .LBB0_1123
	s_waitcnt lgkmcnt(0)
	v_mfma_f32_16x16x32_bf16 v[44:47], v[140:143], v[160:163], v[44:47]
	v_mfma_f32_16x16x32_bf16 v[40:43], v[140:143], v[168:171], v[40:43]
	v_mfma_f32_16x16x32_bf16 v[28:31], v[136:139], v[160:163], v[28:31]
	v_mfma_f32_16x16x32_bf16 v[24:27], v[136:139], v[168:171], v[24:27]
	v_mfma_f32_16x16x32_bf16 v[12:15], v[132:135], v[160:163], v[12:15]
	v_mfma_f32_16x16x32_bf16 v[8:11], v[132:135], v[168:171], v[8:11]
	v_mfma_f32_16x16x32_bf16 v[4:7], v[128:131], v[160:163], v[4:7]
	v_mfma_f32_16x16x32_bf16 v[0:3], v[128:131], v[168:171], v[0:3]
	v_mfma_f32_16x16x32_bf16 v[44:47], v[156:159], v[164:167], v[44:47]
	v_mfma_f32_16x16x32_bf16 v[40:43], v[156:159], v[172:175], v[40:43]
	v_mfma_f32_16x16x32_bf16 v[28:31], v[152:155], v[164:167], v[28:31]
	v_mfma_f32_16x16x32_bf16 v[24:27], v[152:155], v[172:175], v[24:27]
	v_mfma_f32_16x16x32_bf16 v[12:15], v[148:151], v[164:167], v[12:15]
	v_mfma_f32_16x16x32_bf16 v[8:11], v[148:151], v[172:175], v[8:11]
	v_mfma_f32_16x16x32_bf16 v[4:7], v[144:147], v[164:167], v[4:7]
	v_mfma_f32_16x16x32_bf16 v[0:3], v[144:147], v[172:175], v[0:3]
	s_branch .LBB0_1123
.LBB0_1136:
	v_readfirstlane_b32 s6, v220
	s_waitcnt lgkmcnt(0)
	v_lshl_add_u64 v[128:129], v[210:211], 0, s[50:51]
	s_mov_b32 m0, s6
	v_readfirstlane_b32 s6, v221
	ds_read_b128 v[192:195], v246
	ds_read_b128 v[196:199], v246 offset:1024
	ds_read_b128 v[200:203], v246 offset:2048
	ds_read_b128 v[204:207], v246 offset:3072
	ds_read_b128 v[172:175], v247
	ds_read_b128 v[188:191], v247 offset:1024
	ds_read_b128 v[168:171], v227
	ds_read_b128 v[184:187], v227 offset:1024
	ds_read_b128 v[164:167], v251
	ds_read_b128 v[180:183], v251 offset:1024
	ds_read_b128 v[160:163], v252
	ds_read_b128 v[176:179], v252 offset:1024
	global_load_lds_dwordx4 v[128:129], off
	v_lshl_add_u64 v[128:129], v[208:209], 0, s[50:51]
	s_mov_b32 m0, s6
	s_nop 0
	global_load_lds_dwordx4 v[128:129], off
	s_barrier
	s_waitcnt lgkmcnt(0)
	v_mfma_f32_16x16x32_bf16 v[124:127], v[172:175], v[192:195], v[124:127]
	v_mfma_f32_16x16x32_bf16 v[120:123], v[172:175], v[200:203], v[120:123]
	v_mfma_f32_16x16x32_bf16 v[116:119], v[168:171], v[192:195], v[116:119]
	v_mfma_f32_16x16x32_bf16 v[112:115], v[168:171], v[200:203], v[112:115]
	v_mfma_f32_16x16x32_bf16 v[108:111], v[164:167], v[192:195], v[108:111]
	v_mfma_f32_16x16x32_bf16 v[104:107], v[164:167], v[200:203], v[104:107]
	v_mfma_f32_16x16x32_bf16 v[100:103], v[160:163], v[192:195], v[100:103]
	v_mfma_f32_16x16x32_bf16 v[96:99], v[160:163], v[200:203], v[96:99]
	v_mfma_f32_16x16x32_bf16 v[124:127], v[188:191], v[196:199], v[124:127]
	v_mfma_f32_16x16x32_bf16 v[120:123], v[188:191], v[204:207], v[120:123]
	v_mfma_f32_16x16x32_bf16 v[116:119], v[184:187], v[196:199], v[116:119]
	v_mfma_f32_16x16x32_bf16 v[112:115], v[184:187], v[204:207], v[112:115]
	v_mfma_f32_16x16x32_bf16 v[144:147], v[180:183], v[196:199], v[108:111]
	v_mfma_f32_16x16x32_bf16 v[148:151], v[180:183], v[204:207], v[104:107]
	v_mfma_f32_16x16x32_bf16 v[152:155], v[176:179], v[196:199], v[100:103]
	v_mfma_f32_16x16x32_bf16 v[156:159], v[176:179], v[204:207], v[96:99]
	s_barrier
	ds_read_b128 v[208:211], v248
	ds_read_b128 v[212:215], v248 offset:1024
	ds_read_b128 v[216:219], v248 offset:2048
	ds_read_b128 v[220:223], v248 offset:3072
	s_barrier
	s_waitcnt lgkmcnt(0)
	v_mfma_f32_16x16x32_bf16 v[92:95], v[172:175], v[208:211], v[92:95]
	v_mfma_f32_16x16x32_bf16 v[88:91], v[172:175], v[216:219], v[88:91]
	v_mfma_f32_16x16x32_bf16 v[84:87], v[168:171], v[208:211], v[84:87]
	v_mfma_f32_16x16x32_bf16 v[80:83], v[168:171], v[216:219], v[80:83]
	v_mfma_f32_16x16x32_bf16 v[76:79], v[164:167], v[208:211], v[76:79]
	v_mfma_f32_16x16x32_bf16 v[72:75], v[164:167], v[216:219], v[72:75]
	v_mfma_f32_16x16x32_bf16 v[68:71], v[160:163], v[208:211], v[68:71]
	v_mfma_f32_16x16x32_bf16 v[64:67], v[160:163], v[216:219], v[64:67]
	v_mfma_f32_16x16x32_bf16 v[96:99], v[188:191], v[212:215], v[92:95]
	v_mfma_f32_16x16x32_bf16 v[100:103], v[188:191], v[220:223], v[88:91]
	v_mfma_f32_16x16x32_bf16 v[104:107], v[184:187], v[212:215], v[84:87]
	v_mfma_f32_16x16x32_bf16 v[108:111], v[184:187], v[220:223], v[80:83]
	v_mfma_f32_16x16x32_bf16 v[128:131], v[180:183], v[212:215], v[76:79]
	v_mfma_f32_16x16x32_bf16 v[132:135], v[180:183], v[220:223], v[72:75]
	v_mfma_f32_16x16x32_bf16 v[136:139], v[176:179], v[212:215], v[68:71]
	v_mfma_f32_16x16x32_bf16 v[140:143], v[176:179], v[220:223], v[64:67]
	s_and_b64 vcc, exec, s[4:5]
	s_barrier
	s_cbranch_vccnz .LBB0_1138
	ds_read_b128 v[172:175], v247 offset:16384
	ds_read_b128 v[188:191], v247 offset:17408
	ds_read_b128 v[168:171], v227 offset:16384
	ds_read_b128 v[184:187], v227 offset:17408
	ds_read_b128 v[164:167], v251 offset:16384
	ds_read_b128 v[180:183], v251 offset:17408
	ds_read_b128 v[160:163], v252 offset:16384
	ds_read_b128 v[176:179], v252 offset:17408
.LBB0_1138:
	s_waitcnt vmcnt(4)
	s_barrier
	s_waitcnt lgkmcnt(0)
	s_and_b64 vcc, exec, s[4:5]
	s_cbranch_vccnz .LBB0_1140
	s_waitcnt lgkmcnt(0)
	v_mfma_f32_16x16x32_bf16 v[60:63], v[172:175], v[192:195], v[60:63]
	v_mfma_f32_16x16x32_bf16 v[56:59], v[172:175], v[200:203], v[56:59]
	v_mfma_f32_16x16x32_bf16 v[52:55], v[168:171], v[192:195], v[52:55]
	v_mfma_f32_16x16x32_bf16 v[48:51], v[168:171], v[200:203], v[48:51]
	v_mfma_f32_16x16x32_bf16 v[36:39], v[164:167], v[192:195], v[36:39]
	v_mfma_f32_16x16x32_bf16 v[32:35], v[164:167], v[200:203], v[32:35]
	v_mfma_f32_16x16x32_bf16 v[20:23], v[160:163], v[192:195], v[20:23]
	v_mfma_f32_16x16x32_bf16 v[16:19], v[160:163], v[200:203], v[16:19]
	v_mfma_f32_16x16x32_bf16 v[60:63], v[188:191], v[196:199], v[60:63]
	v_mfma_f32_16x16x32_bf16 v[56:59], v[188:191], v[204:207], v[56:59]
	v_mfma_f32_16x16x32_bf16 v[52:55], v[184:187], v[196:199], v[52:55]
	v_mfma_f32_16x16x32_bf16 v[48:51], v[184:187], v[204:207], v[48:51]
	v_mfma_f32_16x16x32_bf16 v[36:39], v[180:183], v[196:199], v[36:39]
	v_mfma_f32_16x16x32_bf16 v[32:35], v[180:183], v[204:207], v[32:35]
	v_mfma_f32_16x16x32_bf16 v[20:23], v[176:179], v[196:199], v[20:23]
	v_mfma_f32_16x16x32_bf16 v[16:19], v[176:179], v[204:207], v[16:19]
	v_mfma_f32_16x16x32_bf16 v[44:47], v[172:175], v[208:211], v[44:47]
	v_mfma_f32_16x16x32_bf16 v[40:43], v[172:175], v[216:219], v[40:43]
	v_mfma_f32_16x16x32_bf16 v[28:31], v[168:171], v[208:211], v[28:31]
	v_mfma_f32_16x16x32_bf16 v[24:27], v[168:171], v[216:219], v[24:27]
	v_mfma_f32_16x16x32_bf16 v[12:15], v[164:167], v[208:211], v[12:15]
	v_mfma_f32_16x16x32_bf16 v[8:11], v[164:167], v[216:219], v[8:11]
	v_mfma_f32_16x16x32_bf16 v[4:7], v[160:163], v[208:211], v[4:7]
	v_mfma_f32_16x16x32_bf16 v[0:3], v[160:163], v[216:219], v[0:3]
	v_mfma_f32_16x16x32_bf16 v[44:47], v[188:191], v[212:215], v[44:47]
	v_mfma_f32_16x16x32_bf16 v[40:43], v[188:191], v[220:223], v[40:43]
	v_mfma_f32_16x16x32_bf16 v[28:31], v[184:187], v[212:215], v[28:31]
	v_mfma_f32_16x16x32_bf16 v[24:27], v[184:187], v[220:223], v[24:27]
	v_mfma_f32_16x16x32_bf16 v[12:15], v[180:183], v[212:215], v[12:15]
	v_mfma_f32_16x16x32_bf16 v[8:11], v[180:183], v[220:223], v[8:11]
	v_mfma_f32_16x16x32_bf16 v[4:7], v[176:179], v[212:215], v[4:7]
	v_mfma_f32_16x16x32_bf16 v[0:3], v[176:179], v[220:223], v[0:3]
.LBB0_1140:
	s_barrier
	ds_read_b128 v[192:195], v249
	ds_read_b128 v[196:199], v249 offset:1024
	ds_read_b128 v[200:203], v249 offset:2048
	ds_read_b128 v[204:207], v249 offset:3072
	s_waitcnt lgkmcnt(0)
	ds_read_b128 v[172:175], v247 offset:32768
	ds_read_b128 v[188:191], v247 offset:33792
	ds_read_b128 v[168:171], v227 offset:32768
	ds_read_b128 v[184:187], v227 offset:33792
	ds_read_b128 v[164:167], v251 offset:32768
	ds_read_b128 v[180:183], v251 offset:33792
	ds_read_b128 v[160:163], v252 offset:32768
	ds_read_b128 v[176:179], v252 offset:33792
	s_waitcnt vmcnt(2)
	s_barrier
	s_waitcnt lgkmcnt(0)
	v_mfma_f32_16x16x32_bf16 v[64:67], v[172:175], v[192:195], v[124:127]
	v_mfma_f32_16x16x32_bf16 v[88:91], v[188:191], v[196:199], v[64:67]
	v_mfma_f32_16x16x32_bf16 v[64:67], v[172:175], v[200:203], v[120:123]
	v_mfma_f32_16x16x32_bf16 v[92:95], v[188:191], v[204:207], v[64:67]
	v_mfma_f32_16x16x32_bf16 v[64:67], v[168:171], v[192:195], v[116:119]
	v_mfma_f32_16x16x32_bf16 v[80:83], v[184:187], v[196:199], v[64:67]
	v_mfma_f32_16x16x32_bf16 v[64:67], v[168:171], v[200:203], v[112:115]
	v_mfma_f32_16x16x32_bf16 v[84:87], v[184:187], v[204:207], v[64:67]
	v_mfma_f32_16x16x32_bf16 v[64:67], v[164:167], v[192:195], v[144:147]
	v_mfma_f32_16x16x32_bf16 v[72:75], v[180:183], v[196:199], v[64:67]
	v_mfma_f32_16x16x32_bf16 v[64:67], v[164:167], v[200:203], v[148:151]
	v_mfma_f32_16x16x32_bf16 v[76:79], v[180:183], v[204:207], v[64:67]
	v_mfma_f32_16x16x32_bf16 v[64:67], v[160:163], v[192:195], v[152:155]
	v_mfma_f32_16x16x32_bf16 v[68:71], v[160:163], v[200:203], v[156:159]
	v_mfma_f32_16x16x32_bf16 v[64:67], v[176:179], v[196:199], v[64:67]
	v_mfma_f32_16x16x32_bf16 v[68:71], v[176:179], v[204:207], v[68:71]
	s_barrier
	ds_read_b128 v[144:147], v250
	ds_read_b128 v[148:151], v250 offset:1024
	ds_read_b128 v[152:155], v250 offset:2048
	ds_read_b128 v[156:159], v250 offset:3072
	s_waitcnt vmcnt(0)
	s_barrier
	s_waitcnt lgkmcnt(0)
	v_mfma_f32_16x16x32_bf16 v[96:99], v[172:175], v[144:147], v[96:99]
	v_mfma_f32_16x16x32_bf16 v[120:123], v[188:191], v[148:151], v[96:99]
	v_mfma_f32_16x16x32_bf16 v[96:99], v[172:175], v[152:155], v[100:103]
	v_mfma_f32_16x16x32_bf16 v[124:127], v[188:191], v[156:159], v[96:99]
	v_mfma_f32_16x16x32_bf16 v[96:99], v[168:171], v[144:147], v[104:107]
	v_mfma_f32_16x16x32_bf16 v[112:115], v[184:187], v[148:151], v[96:99]
	v_mfma_f32_16x16x32_bf16 v[96:99], v[168:171], v[152:155], v[108:111]
	v_mfma_f32_16x16x32_bf16 v[116:119], v[184:187], v[156:159], v[96:99]
	v_mfma_f32_16x16x32_bf16 v[96:99], v[164:167], v[144:147], v[128:131]
	v_mfma_f32_16x16x32_bf16 v[104:107], v[180:183], v[148:151], v[96:99]
	v_mfma_f32_16x16x32_bf16 v[96:99], v[164:167], v[152:155], v[132:135]
	v_mfma_f32_16x16x32_bf16 v[108:111], v[180:183], v[156:159], v[96:99]
	v_mfma_f32_16x16x32_bf16 v[96:99], v[160:163], v[144:147], v[136:139]
	v_mfma_f32_16x16x32_bf16 v[100:103], v[160:163], v[152:155], v[140:143]
	v_mfma_f32_16x16x32_bf16 v[96:99], v[176:179], v[148:151], v[96:99]
	v_mfma_f32_16x16x32_bf16 v[100:103], v[176:179], v[156:159], v[100:103]
	s_and_b64 vcc, exec, s[4:5]
	s_barrier
	s_cbranch_vccnz .LBB0_1142
	ds_read_b128 v[172:175], v247 offset:49152
	ds_read_b128 v[188:191], v247 offset:50176
	ds_read_b128 v[168:171], v227 offset:49152
	ds_read_b128 v[184:187], v227 offset:50176
	ds_read_b128 v[164:167], v251 offset:49152
	ds_read_b128 v[180:183], v251 offset:50176
	ds_read_b128 v[160:163], v252 offset:49152
	ds_read_b128 v[176:179], v252 offset:50176
.LBB0_1142:
	s_barrier
	s_waitcnt lgkmcnt(0)
	s_and_b64 vcc, exec, s[4:5]
	s_cbranch_vccnz .LBB0_1144
	s_waitcnt lgkmcnt(0)
	v_mfma_f32_16x16x32_bf16 v[60:63], v[172:175], v[192:195], v[60:63]
	v_mfma_f32_16x16x32_bf16 v[56:59], v[172:175], v[200:203], v[56:59]
	v_mfma_f32_16x16x32_bf16 v[52:55], v[168:171], v[192:195], v[52:55]
	v_mfma_f32_16x16x32_bf16 v[48:51], v[168:171], v[200:203], v[48:51]
	v_mfma_f32_16x16x32_bf16 v[36:39], v[164:167], v[192:195], v[36:39]
	v_mfma_f32_16x16x32_bf16 v[32:35], v[164:167], v[200:203], v[32:35]
	v_mfma_f32_16x16x32_bf16 v[20:23], v[160:163], v[192:195], v[20:23]
	v_mfma_f32_16x16x32_bf16 v[16:19], v[160:163], v[200:203], v[16:19]
	v_mfma_f32_16x16x32_bf16 v[60:63], v[188:191], v[196:199], v[60:63]
	v_mfma_f32_16x16x32_bf16 v[56:59], v[188:191], v[204:207], v[56:59]
	v_mfma_f32_16x16x32_bf16 v[52:55], v[184:187], v[196:199], v[52:55]
	v_mfma_f32_16x16x32_bf16 v[48:51], v[184:187], v[204:207], v[48:51]
	v_mfma_f32_16x16x32_bf16 v[36:39], v[180:183], v[196:199], v[36:39]
	v_mfma_f32_16x16x32_bf16 v[32:35], v[180:183], v[204:207], v[32:35]
	v_mfma_f32_16x16x32_bf16 v[20:23], v[176:179], v[196:199], v[20:23]
	v_mfma_f32_16x16x32_bf16 v[16:19], v[176:179], v[204:207], v[16:19]
	v_mfma_f32_16x16x32_bf16 v[44:47], v[172:175], v[144:147], v[44:47]
	v_mfma_f32_16x16x32_bf16 v[40:43], v[172:175], v[152:155], v[40:43]
	v_mfma_f32_16x16x32_bf16 v[28:31], v[168:171], v[144:147], v[28:31]
	v_mfma_f32_16x16x32_bf16 v[24:27], v[168:171], v[152:155], v[24:27]
	v_mfma_f32_16x16x32_bf16 v[12:15], v[164:167], v[144:147], v[12:15]
	v_mfma_f32_16x16x32_bf16 v[8:11], v[164:167], v[152:155], v[8:11]
	v_mfma_f32_16x16x32_bf16 v[4:7], v[160:163], v[144:147], v[4:7]
	v_mfma_f32_16x16x32_bf16 v[0:3], v[160:163], v[152:155], v[0:3]
	v_mfma_f32_16x16x32_bf16 v[44:47], v[188:191], v[148:151], v[44:47]
	v_mfma_f32_16x16x32_bf16 v[40:43], v[188:191], v[156:159], v[40:43]
	v_mfma_f32_16x16x32_bf16 v[28:31], v[184:187], v[148:151], v[28:31]
	v_mfma_f32_16x16x32_bf16 v[24:27], v[184:187], v[156:159], v[24:27]
	v_mfma_f32_16x16x32_bf16 v[12:15], v[180:183], v[148:151], v[12:15]
	v_mfma_f32_16x16x32_bf16 v[8:11], v[180:183], v[156:159], v[8:11]
	v_mfma_f32_16x16x32_bf16 v[4:7], v[176:179], v[148:151], v[4:7]
	v_mfma_f32_16x16x32_bf16 v[0:3], v[176:179], v[156:159], v[0:3]

.LBB0_1471:
	ds_read_b128 v[166:169], v152
	ds_read_b128 v[170:173], v152 offset:1024
	ds_read_b128 v[174:177], v152 offset:2048
	ds_read_b128 v[178:181], v152 offset:3072
	v_add_u32_e32 v164, 0xc000, v144
	v_lshl_add_u64 v[222:223], s[26:27], 0, v[136:137]
	v_readfirstlane_b32 s19, v164
	v_add_u32_e32 v165, 0xe000, v144
	v_add_u32_e32 v162, s48, v141
	v_add_u32_e32 v163, s49, v141
	v_lshl_add_u64 v[214:215], v[222:223], 0, s[10:11]
	s_mov_b32 m0, s19
	v_lshl_add_u64 v[234:235], s[26:27], 0, v[138:139]
	v_readfirstlane_b32 s19, v165
	ds_read_b128 v[182:185], v153
	ds_read_b128 v[186:189], v153 offset:1024
	ds_read_b128 v[190:193], v154
	ds_read_b128 v[194:197], v154 offset:1024
	ds_read_b128 v[198:201], v162
	ds_read_b128 v[202:205], v162 offset:1024
	ds_read_b128 v[206:209], v163
	ds_read_b128 v[210:213], v163 offset:1024
	global_load_lds_dwordx4 v[214:215], off
	v_lshl_add_u64 v[214:215], v[234:235], 0, s[10:11]
	s_mov_b32 m0, s19
	s_nop 0
	global_load_lds_dwordx4 v[214:215], off
	s_waitcnt lgkmcnt(8)
	s_barrier
	s_waitcnt lgkmcnt(0)
	v_mfma_f32_16x16x32_bf16 v[124:127], v[182:185], v[166:169], v[124:127]
	v_mfma_f32_16x16x32_bf16 v[120:123], v[182:185], v[174:177], v[120:123]
	v_mfma_f32_16x16x32_bf16 v[116:119], v[190:193], v[166:169], v[116:119]
	v_mfma_f32_16x16x32_bf16 v[112:115], v[190:193], v[174:177], v[112:115]
	v_mfma_f32_16x16x32_bf16 v[108:111], v[198:201], v[166:169], v[108:111]
	v_mfma_f32_16x16x32_bf16 v[104:107], v[198:201], v[174:177], v[104:107]
	v_mfma_f32_16x16x32_bf16 v[100:103], v[206:209], v[166:169], v[100:103]
	v_mfma_f32_16x16x32_bf16 v[96:99], v[206:209], v[174:177], v[96:99]
	v_mfma_f32_16x16x32_bf16 v[124:127], v[186:189], v[170:173], v[124:127]
	v_mfma_f32_16x16x32_bf16 v[120:123], v[186:189], v[178:181], v[120:123]
	v_mfma_f32_16x16x32_bf16 v[116:119], v[194:197], v[170:173], v[116:119]
	v_mfma_f32_16x16x32_bf16 v[112:115], v[194:197], v[178:181], v[112:115]
	v_mfma_f32_16x16x32_bf16 v[108:111], v[202:205], v[170:173], v[108:111]
	v_mfma_f32_16x16x32_bf16 v[104:107], v[202:205], v[178:181], v[104:107]
	v_mfma_f32_16x16x32_bf16 v[100:103], v[210:213], v[170:173], v[100:103]
	v_mfma_f32_16x16x32_bf16 v[96:99], v[210:213], v[178:181], v[96:99]
	s_barrier
	v_lshl_add_u64 v[236:237], s[26:27], 0, v[132:133]
	v_readfirstlane_b32 s19, v142
	v_lshl_add_u64 v[238:239], v[236:237], 0, s[12:13]
	s_mov_b32 m0, s19
	ds_read_b128 v[214:217], v159
	ds_read_b128 v[218:221], v159 offset:1024
	ds_read_b128 v[226:229], v159 offset:2048
	ds_read_b128 v[230:233], v159 offset:3072
	global_load_lds_dwordx4 v[238:239], off
	v_lshl_add_u64 v[238:239], s[26:27], 0, v[134:135]
	v_readfirstlane_b32 s19, v143
	v_lshl_add_u64 v[240:241], v[238:239], 0, s[12:13]
	s_mov_b32 m0, s19
	s_nop 0
	global_load_lds_dwordx4 v[240:241], off
	s_barrier
	s_waitcnt lgkmcnt(0)
	v_mfma_f32_16x16x32_bf16 v[92:95], v[182:185], v[214:217], v[92:95]
	v_mfma_f32_16x16x32_bf16 v[88:91], v[182:185], v[226:229], v[88:91]
	v_mfma_f32_16x16x32_bf16 v[84:87], v[190:193], v[214:217], v[84:87]
	v_mfma_f32_16x16x32_bf16 v[80:83], v[190:193], v[226:229], v[80:83]
	v_mfma_f32_16x16x32_bf16 v[76:79], v[198:201], v[214:217], v[76:79]
	v_mfma_f32_16x16x32_bf16 v[72:75], v[198:201], v[226:229], v[72:75]
	v_mfma_f32_16x16x32_bf16 v[68:71], v[206:209], v[214:217], v[68:71]
	v_mfma_f32_16x16x32_bf16 v[64:67], v[206:209], v[226:229], v[64:67]
	v_mfma_f32_16x16x32_bf16 v[92:95], v[186:189], v[218:221], v[92:95]
	v_mfma_f32_16x16x32_bf16 v[88:91], v[186:189], v[230:233], v[88:91]
	v_mfma_f32_16x16x32_bf16 v[84:87], v[194:197], v[218:221], v[84:87]
	v_mfma_f32_16x16x32_bf16 v[80:83], v[194:197], v[230:233], v[80:83]
	v_mfma_f32_16x16x32_bf16 v[76:79], v[202:205], v[218:221], v[76:79]
	v_mfma_f32_16x16x32_bf16 v[72:75], v[202:205], v[230:233], v[72:75]
	v_mfma_f32_16x16x32_bf16 v[68:71], v[210:213], v[218:221], v[68:71]
	v_mfma_f32_16x16x32_bf16 v[64:67], v[210:213], v[230:233], v[64:67]
	v_readfirstlane_b32 s19, v144
	v_lshl_add_u64 v[240:241], v[222:223], 0, s[14:15]
	s_mov_b32 m0, s19
	v_readfirstlane_b32 s19, v145
	s_barrier
	ds_read_b128 v[182:185], v153 offset:16384
	ds_read_b128 v[186:189], v153 offset:17408
	ds_read_b128 v[190:193], v154 offset:16384
	ds_read_b128 v[194:197], v154 offset:17408
	ds_read_b128 v[198:201], v162 offset:16384
	ds_read_b128 v[202:205], v162 offset:17408
	ds_read_b128 v[206:209], v163 offset:16384
	ds_read_b128 v[210:213], v163 offset:17408
	global_load_lds_dwordx4 v[240:241], off
	v_lshl_add_u64 v[240:241], v[234:235], 0, s[14:15]
	s_mov_b32 m0, s19
	s_nop 0
	global_load_lds_dwordx4 v[240:241], off
	s_barrier
	s_waitcnt lgkmcnt(0)
	v_mfma_f32_16x16x32_bf16 v[60:63], v[182:185], v[166:169], v[60:63]
	v_mfma_f32_16x16x32_bf16 v[56:59], v[182:185], v[174:177], v[56:59]
	v_mfma_f32_16x16x32_bf16 v[52:55], v[190:193], v[166:169], v[52:55]
	v_mfma_f32_16x16x32_bf16 v[48:51], v[190:193], v[174:177], v[48:51]
	v_mfma_f32_16x16x32_bf16 v[44:47], v[198:201], v[166:169], v[44:47]
	v_mfma_f32_16x16x32_bf16 v[40:43], v[198:201], v[174:177], v[40:43]
	v_mfma_f32_16x16x32_bf16 v[36:39], v[206:209], v[166:169], v[36:39]
	v_mfma_f32_16x16x32_bf16 v[32:35], v[206:209], v[174:177], v[32:35]
	v_mfma_f32_16x16x32_bf16 v[60:63], v[186:189], v[170:173], v[60:63]
	v_mfma_f32_16x16x32_bf16 v[56:59], v[186:189], v[178:181], v[56:59]
	v_mfma_f32_16x16x32_bf16 v[52:55], v[194:197], v[170:173], v[52:55]
	v_mfma_f32_16x16x32_bf16 v[48:51], v[194:197], v[178:181], v[48:51]
	v_mfma_f32_16x16x32_bf16 v[44:47], v[202:205], v[170:173], v[44:47]
	v_mfma_f32_16x16x32_bf16 v[40:43], v[202:205], v[178:181], v[40:43]
	v_mfma_f32_16x16x32_bf16 v[36:39], v[210:213], v[170:173], v[36:39]
	v_mfma_f32_16x16x32_bf16 v[32:35], v[210:213], v[178:181], v[32:35]
	s_barrier
	v_readfirstlane_b32 s19, v146
	v_lshl_add_u64 v[166:167], v[236:237], 0, s[16:17]
	s_mov_b32 m0, s19
	v_readfirstlane_b32 s19, v147
	global_load_lds_dwordx4 v[166:167], off
	v_lshl_add_u64 v[166:167], v[238:239], 0, s[16:17]
	s_mov_b32 m0, s19
	s_nop 0
	global_load_lds_dwordx4 v[166:167], off
	s_waitcnt vmcnt(6)
	s_barrier
	v_mfma_f32_16x16x32_bf16 v[28:31], v[182:185], v[214:217], v[28:31]
	v_mfma_f32_16x16x32_bf16 v[24:27], v[182:185], v[226:229], v[24:27]
	v_mfma_f32_16x16x32_bf16 v[20:23], v[190:193], v[214:217], v[20:23]
	v_mfma_f32_16x16x32_bf16 v[16:19], v[190:193], v[226:229], v[16:19]
	v_mfma_f32_16x16x32_bf16 v[12:15], v[198:201], v[214:217], v[12:15]
	v_mfma_f32_16x16x32_bf16 v[8:11], v[198:201], v[226:229], v[8:11]
	v_mfma_f32_16x16x32_bf16 v[4:7], v[206:209], v[214:217], v[4:7]
	v_mfma_f32_16x16x32_bf16 v[0:3], v[206:209], v[226:229], v[0:3]
	v_mfma_f32_16x16x32_bf16 v[28:31], v[186:189], v[218:221], v[28:31]
	v_mfma_f32_16x16x32_bf16 v[24:27], v[186:189], v[230:233], v[24:27]
	v_mfma_f32_16x16x32_bf16 v[20:23], v[194:197], v[218:221], v[20:23]
	v_mfma_f32_16x16x32_bf16 v[16:19], v[194:197], v[230:233], v[16:19]
	v_mfma_f32_16x16x32_bf16 v[12:15], v[202:205], v[218:221], v[12:15]
	v_mfma_f32_16x16x32_bf16 v[8:11], v[202:205], v[230:233], v[8:11]
	v_mfma_f32_16x16x32_bf16 v[4:7], v[210:213], v[218:221], v[4:7]
	v_mfma_f32_16x16x32_bf16 v[0:3], v[210:213], v[230:233], v[0:3]
	s_barrier
	ds_read_b128 v[166:169], v160
	ds_read_b128 v[170:173], v160 offset:1024
	ds_read_b128 v[174:177], v160 offset:2048
	ds_read_b128 v[178:181], v160 offset:3072
	v_readfirstlane_b32 s19, v148
	v_lshl_add_u64 v[214:215], v[222:223], 0, s[20:21]
	s_mov_b32 m0, s19
	v_readfirstlane_b32 s19, v149
	ds_read_b128 v[182:185], v153 offset:32768
	ds_read_b128 v[186:189], v153 offset:33792
	ds_read_b128 v[190:193], v154 offset:32768
	ds_read_b128 v[194:197], v154 offset:33792
	ds_read_b128 v[198:201], v162 offset:32768
	ds_read_b128 v[202:205], v162 offset:33792
	ds_read_b128 v[206:209], v163 offset:32768
	ds_read_b128 v[210:213], v163 offset:33792
	global_load_lds_dwordx4 v[214:215], off
	v_lshl_add_u64 v[214:215], v[234:235], 0, s[20:21]
	s_mov_b32 m0, s19
	s_nop 0
	global_load_lds_dwordx4 v[214:215], off
	s_waitcnt lgkmcnt(8)
	s_barrier
	s_waitcnt lgkmcnt(0)
	v_mfma_f32_16x16x32_bf16 v[124:127], v[182:185], v[166:169], v[124:127]
	v_mfma_f32_16x16x32_bf16 v[120:123], v[182:185], v[174:177], v[120:123]
	v_mfma_f32_16x16x32_bf16 v[116:119], v[190:193], v[166:169], v[116:119]
	v_mfma_f32_16x16x32_bf16 v[112:115], v[190:193], v[174:177], v[112:115]
	v_mfma_f32_16x16x32_bf16 v[108:111], v[198:201], v[166:169], v[108:111]
	v_mfma_f32_16x16x32_bf16 v[104:107], v[198:201], v[174:177], v[104:107]
	v_mfma_f32_16x16x32_bf16 v[100:103], v[206:209], v[166:169], v[100:103]
	v_mfma_f32_16x16x32_bf16 v[96:99], v[206:209], v[174:177], v[96:99]
	v_mfma_f32_16x16x32_bf16 v[124:127], v[186:189], v[170:173], v[124:127]
	v_mfma_f32_16x16x32_bf16 v[120:123], v[186:189], v[178:181], v[120:123]
	v_mfma_f32_16x16x32_bf16 v[116:119], v[194:197], v[170:173], v[116:119]
	v_mfma_f32_16x16x32_bf16 v[112:115], v[194:197], v[178:181], v[112:115]
	v_mfma_f32_16x16x32_bf16 v[108:111], v[202:205], v[170:173], v[108:111]
	v_mfma_f32_16x16x32_bf16 v[104:107], v[202:205], v[178:181], v[104:107]
	v_mfma_f32_16x16x32_bf16 v[100:103], v[210:213], v[170:173], v[100:103]
	v_mfma_f32_16x16x32_bf16 v[96:99], v[210:213], v[178:181], v[96:99]
	s_barrier
	v_readfirstlane_b32 s19, v155
	v_lshl_add_u64 v[240:241], v[236:237], 0, s[22:23]
	s_mov_b32 m0, s19
	v_readfirstlane_b32 s19, v156
	ds_read_b128 v[214:217], v161
	ds_read_b128 v[218:221], v161 offset:1024
	ds_read_b128 v[226:229], v161 offset:2048
	ds_read_b128 v[230:233], v161 offset:3072
	global_load_lds_dwordx4 v[240:241], off
	v_lshl_add_u64 v[240:241], v[238:239], 0, s[22:23]
	s_mov_b32 m0, s19
	s_nop 0
	global_load_lds_dwordx4 v[240:241], off
	s_barrier
	s_waitcnt lgkmcnt(0)
	v_mfma_f32_16x16x32_bf16 v[92:95], v[182:185], v[214:217], v[92:95]
	v_mfma_f32_16x16x32_bf16 v[88:91], v[182:185], v[226:229], v[88:91]
	v_mfma_f32_16x16x32_bf16 v[84:87], v[190:193], v[214:217], v[84:87]
	v_mfma_f32_16x16x32_bf16 v[80:83], v[190:193], v[226:229], v[80:83]
	v_mfma_f32_16x16x32_bf16 v[76:79], v[198:201], v[214:217], v[76:79]
	v_mfma_f32_16x16x32_bf16 v[72:75], v[198:201], v[226:229], v[72:75]
	v_mfma_f32_16x16x32_bf16 v[68:71], v[206:209], v[214:217], v[68:71]
	v_mfma_f32_16x16x32_bf16 v[64:67], v[206:209], v[226:229], v[64:67]
	v_mfma_f32_16x16x32_bf16 v[92:95], v[186:189], v[218:221], v[92:95]
	v_mfma_f32_16x16x32_bf16 v[88:91], v[186:189], v[230:233], v[88:91]
	v_mfma_f32_16x16x32_bf16 v[84:87], v[194:197], v[218:221], v[84:87]
	v_mfma_f32_16x16x32_bf16 v[80:83], v[194:197], v[230:233], v[80:83]
	v_mfma_f32_16x16x32_bf16 v[76:79], v[202:205], v[218:221], v[76:79]
	v_mfma_f32_16x16x32_bf16 v[72:75], v[202:205], v[230:233], v[72:75]
	v_mfma_f32_16x16x32_bf16 v[68:71], v[210:213], v[218:221], v[68:71]
	v_mfma_f32_16x16x32_bf16 v[64:67], v[210:213], v[230:233], v[64:67]
	v_readfirstlane_b32 s19, v150
	v_lshl_add_u64 v[222:223], v[222:223], 0, s[34:35]
	s_mov_b32 m0, s19
	v_readfirstlane_b32 s19, v151
	s_barrier
	ds_read_b128 v[182:185], v153 offset:49152
	ds_read_b128 v[186:189], v153 offset:50176
	ds_read_b128 v[190:193], v154 offset:49152
	ds_read_b128 v[194:197], v154 offset:50176
	ds_read_b128 v[198:201], v162 offset:49152
	ds_read_b128 v[202:205], v162 offset:50176
	ds_read_b128 v[206:209], v163 offset:49152
	ds_read_b128 v[210:213], v163 offset:50176
	global_load_lds_dwordx4 v[222:223], off
	v_lshl_add_u64 v[222:223], v[234:235], 0, s[34:35]
	s_mov_b32 m0, s19
	s_nop 0
	global_load_lds_dwordx4 v[222:223], off
	s_barrier
	s_waitcnt lgkmcnt(0)
	v_mfma_f32_16x16x32_bf16 v[60:63], v[182:185], v[166:169], v[60:63]
	v_mfma_f32_16x16x32_bf16 v[56:59], v[182:185], v[174:177], v[56:59]
	v_mfma_f32_16x16x32_bf16 v[52:55], v[190:193], v[166:169], v[52:55]
	v_mfma_f32_16x16x32_bf16 v[48:51], v[190:193], v[174:177], v[48:51]
	v_mfma_f32_16x16x32_bf16 v[44:47], v[198:201], v[166:169], v[44:47]
	v_mfma_f32_16x16x32_bf16 v[40:43], v[198:201], v[174:177], v[40:43]
	v_mfma_f32_16x16x32_bf16 v[36:39], v[206:209], v[166:169], v[36:39]
	v_mfma_f32_16x16x32_bf16 v[32:35], v[206:209], v[174:177], v[32:35]
	v_mfma_f32_16x16x32_bf16 v[60:63], v[186:189], v[170:173], v[60:63]
	v_mfma_f32_16x16x32_bf16 v[56:59], v[186:189], v[178:181], v[56:59]
	v_mfma_f32_16x16x32_bf16 v[52:55], v[194:197], v[170:173], v[52:55]
	v_mfma_f32_16x16x32_bf16 v[48:51], v[194:197], v[178:181], v[48:51]
	v_mfma_f32_16x16x32_bf16 v[44:47], v[202:205], v[170:173], v[44:47]
	v_mfma_f32_16x16x32_bf16 v[40:43], v[202:205], v[178:181], v[40:43]
	v_mfma_f32_16x16x32_bf16 v[36:39], v[210:213], v[170:173], v[36:39]
	v_mfma_f32_16x16x32_bf16 v[32:35], v[210:213], v[178:181], v[32:35]
	s_barrier
	v_readfirstlane_b32 s19, v157
	v_lshl_add_u64 v[166:167], v[236:237], 0, s[36:37]
	s_mov_b32 m0, s19
	v_readfirstlane_b32 s19, v158
	global_load_lds_dwordx4 v[166:167], off
	v_lshl_add_u64 v[166:167], v[238:239], 0, s[36:37]
	s_mov_b32 m0, s19
	s_nop 0
	global_load_lds_dwordx4 v[166:167], off
	s_waitcnt vmcnt(6)
	s_barrier
	v_mfma_f32_16x16x32_bf16 v[28:31], v[182:185], v[214:217], v[28:31]
	v_mfma_f32_16x16x32_bf16 v[24:27], v[182:185], v[226:229], v[24:27]
	v_mfma_f32_16x16x32_bf16 v[20:23], v[190:193], v[214:217], v[20:23]
	v_mfma_f32_16x16x32_bf16 v[16:19], v[190:193], v[226:229], v[16:19]
	v_mfma_f32_16x16x32_bf16 v[12:15], v[198:201], v[214:217], v[12:15]
	v_mfma_f32_16x16x32_bf16 v[8:11], v[198:201], v[226:229], v[8:11]
	v_mfma_f32_16x16x32_bf16 v[4:7], v[206:209], v[214:217], v[4:7]
	v_mfma_f32_16x16x32_bf16 v[0:3], v[206:209], v[226:229], v[0:3]
	v_mfma_f32_16x16x32_bf16 v[28:31], v[186:189], v[218:221], v[28:31]
	v_mfma_f32_16x16x32_bf16 v[24:27], v[186:189], v[230:233], v[24:27]
	v_mfma_f32_16x16x32_bf16 v[20:23], v[194:197], v[218:221], v[20:23]
	v_mfma_f32_16x16x32_bf16 v[16:19], v[194:197], v[230:233], v[16:19]
	v_mfma_f32_16x16x32_bf16 v[12:15], v[202:205], v[218:221], v[12:15]
	v_mfma_f32_16x16x32_bf16 v[8:11], v[202:205], v[230:233], v[8:11]
	v_mfma_f32_16x16x32_bf16 v[4:7], v[210:213], v[218:221], v[4:7]
	v_mfma_f32_16x16x32_bf16 v[0:3], v[210:213], v[230:233], v[0:3]
	s_add_i32 s18, s18, 2
	s_add_u32 s26, s26, 0x100
	s_addc_u32 s27, s27, 0
	s_cmpk_lt_u32 s18, 0x54
	s_barrier
	s_cbranch_scc1 .LBB0_1471
	s_add_u32 s18, s24, 0x2b80
	s_addc_u32 s19, s25, 0
	v_readfirstlane_b32 s24, v164
	v_lshl_add_u64 v[206:207], s[18:19], 0, v[130:131]
	s_mov_b32 m0, s24
	ds_read_b128 v[132:135], v152
	ds_read_b128 v[136:139], v152 offset:1024
	ds_read_b128 v[166:169], v152 offset:2048
	ds_read_b128 v[170:173], v152 offset:3072
	ds_read_b128 v[174:177], v153
	ds_read_b128 v[178:181], v153 offset:1024
	ds_read_b128 v[182:185], v154
	ds_read_b128 v[186:189], v154 offset:1024
	ds_read_b128 v[190:193], v162
	ds_read_b128 v[194:197], v162 offset:1024
	ds_read_b128 v[198:201], v163
	ds_read_b128 v[202:205], v163 offset:1024
	global_load_lds_dwordx4 v[206:207], off
	v_lshl_add_u64 v[206:207], s[18:19], 0, v[128:129]
	v_readfirstlane_b32 s18, v165
	s_mov_b32 m0, s18
	s_nop 0
	global_load_lds_dwordx4 v[206:207], off
	s_barrier
	s_waitcnt lgkmcnt(0)
	v_mfma_f32_16x16x32_bf16 v[124:127], v[174:177], v[132:135], v[124:127]
	v_mfma_f32_16x16x32_bf16 v[120:123], v[174:177], v[166:169], v[120:123]
	v_mfma_f32_16x16x32_bf16 v[116:119], v[182:185], v[132:135], v[116:119]
	v_mfma_f32_16x16x32_bf16 v[112:115], v[182:185], v[166:169], v[112:115]
	v_mfma_f32_16x16x32_bf16 v[124:127], v[178:181], v[136:139], v[124:127]
	v_mfma_f32_16x16x32_bf16 v[120:123], v[178:181], v[170:173], v[120:123]
	v_mfma_f32_16x16x32_bf16 v[116:119], v[186:189], v[136:139], v[116:119]
	v_mfma_f32_16x16x32_bf16 v[112:115], v[186:189], v[170:173], v[112:115]
	v_mfma_f32_16x16x32_bf16 v[108:111], v[190:193], v[132:135], v[108:111]
	v_mfma_f32_16x16x32_bf16 v[104:107], v[190:193], v[166:169], v[104:107]
	v_mfma_f32_16x16x32_bf16 v[100:103], v[198:201], v[132:135], v[100:103]
	v_mfma_f32_16x16x32_bf16 v[96:99], v[198:201], v[166:169], v[96:99]
	v_mfma_f32_16x16x32_bf16 v[206:209], v[194:197], v[136:139], v[108:111]
	v_mfma_f32_16x16x32_bf16 v[210:213], v[194:197], v[170:173], v[104:107]
	v_mfma_f32_16x16x32_bf16 v[214:217], v[202:205], v[136:139], v[100:103]
	v_mfma_f32_16x16x32_bf16 v[218:221], v[202:205], v[170:173], v[96:99]
	s_barrier
	s_nop 1
	ds_read_b128 v[96:99], v159
	ds_read_b128 v[100:103], v159 offset:1024
	ds_read_b128 v[104:107], v159 offset:2048
	ds_read_b128 v[108:111], v159 offset:3072
	s_barrier
	s_waitcnt lgkmcnt(0)
	v_mfma_f32_16x16x32_bf16 v[92:95], v[174:177], v[96:99], v[92:95]
	v_mfma_f32_16x16x32_bf16 v[88:91], v[174:177], v[104:107], v[88:91]
	v_mfma_f32_16x16x32_bf16 v[84:87], v[182:185], v[96:99], v[84:87]
	v_mfma_f32_16x16x32_bf16 v[80:83], v[182:185], v[104:107], v[80:83]
	v_mfma_f32_16x16x32_bf16 v[92:95], v[178:181], v[100:103], v[92:95]
	v_mfma_f32_16x16x32_bf16 v[88:91], v[178:181], v[108:111], v[88:91]
	v_mfma_f32_16x16x32_bf16 v[84:87], v[186:189], v[100:103], v[84:87]
	v_mfma_f32_16x16x32_bf16 v[80:83], v[186:189], v[108:111], v[80:83]
	v_mfma_f32_16x16x32_bf16 v[76:79], v[190:193], v[96:99], v[76:79]
	v_mfma_f32_16x16x32_bf16 v[72:75], v[190:193], v[104:107], v[72:75]
	v_mfma_f32_16x16x32_bf16 v[68:71], v[198:201], v[96:99], v[68:71]
	v_mfma_f32_16x16x32_bf16 v[64:67], v[198:201], v[104:107], v[64:67]
	v_mfma_f32_16x16x32_bf16 v[174:177], v[194:197], v[100:103], v[76:79]
	v_mfma_f32_16x16x32_bf16 v[178:181], v[194:197], v[108:111], v[72:75]
	v_mfma_f32_16x16x32_bf16 v[182:185], v[202:205], v[100:103], v[68:71]
	v_mfma_f32_16x16x32_bf16 v[186:189], v[202:205], v[108:111], v[64:67]
	s_barrier
	s_nop 1
	ds_read_b128 v[64:67], v153 offset:16384
	ds_read_b128 v[68:71], v153 offset:17408
	ds_read_b128 v[72:75], v154 offset:16384
	ds_read_b128 v[76:79], v154 offset:17408
	ds_read_b128 v[190:193], v162 offset:16384
	ds_read_b128 v[194:197], v162 offset:17408
	ds_read_b128 v[198:201], v163 offset:16384
	ds_read_b128 v[202:205], v163 offset:17408
	s_waitcnt vmcnt(4)
	s_barrier
	s_waitcnt lgkmcnt(0)
	v_mfma_f32_16x16x32_bf16 v[60:63], v[64:67], v[132:135], v[60:63]
	v_mfma_f32_16x16x32_bf16 v[56:59], v[64:67], v[166:169], v[56:59]
	v_mfma_f32_16x16x32_bf16 v[52:55], v[72:75], v[132:135], v[52:55]
	v_mfma_f32_16x16x32_bf16 v[48:51], v[72:75], v[166:169], v[48:51]
	v_mfma_f32_16x16x32_bf16 v[60:63], v[68:71], v[136:139], v[60:63]
	v_mfma_f32_16x16x32_bf16 v[56:59], v[68:71], v[170:173], v[56:59]
	v_mfma_f32_16x16x32_bf16 v[52:55], v[76:79], v[136:139], v[52:55]
	v_mfma_f32_16x16x32_bf16 v[48:51], v[76:79], v[170:173], v[48:51]
	v_mfma_f32_16x16x32_bf16 v[44:47], v[190:193], v[132:135], v[44:47]
	v_mfma_f32_16x16x32_bf16 v[40:43], v[190:193], v[166:169], v[40:43]
	v_mfma_f32_16x16x32_bf16 v[36:39], v[198:201], v[132:135], v[36:39]
	v_mfma_f32_16x16x32_bf16 v[32:35], v[198:201], v[166:169], v[32:35]
	v_mfma_f32_16x16x32_bf16 v[226:229], v[194:197], v[136:139], v[44:47]
	v_mfma_f32_16x16x32_bf16 v[230:233], v[194:197], v[170:173], v[40:43]
	v_mfma_f32_16x16x32_bf16 v[132:135], v[202:205], v[136:139], v[36:39]
	v_mfma_f32_16x16x32_bf16 v[136:139], v[202:205], v[170:173], v[32:35]
	v_mfma_f32_16x16x32_bf16 v[28:31], v[64:67], v[96:99], v[28:31]
	v_mfma_f32_16x16x32_bf16 v[24:27], v[64:67], v[104:107], v[24:27]
	v_mfma_f32_16x16x32_bf16 v[20:23], v[72:75], v[96:99], v[20:23]
	v_mfma_f32_16x16x32_bf16 v[16:19], v[72:75], v[104:107], v[16:19]
	v_mfma_f32_16x16x32_bf16 v[28:31], v[68:71], v[100:103], v[28:31]
	v_mfma_f32_16x16x32_bf16 v[24:27], v[68:71], v[108:111], v[24:27]
	v_mfma_f32_16x16x32_bf16 v[20:23], v[76:79], v[100:103], v[20:23]
	v_mfma_f32_16x16x32_bf16 v[16:19], v[76:79], v[108:111], v[16:19]
	v_mfma_f32_16x16x32_bf16 v[12:15], v[190:193], v[96:99], v[12:15]
	v_mfma_f32_16x16x32_bf16 v[8:11], v[190:193], v[104:107], v[8:11]
	v_mfma_f32_16x16x32_bf16 v[4:7], v[198:201], v[96:99], v[4:7]
	v_mfma_f32_16x16x32_bf16 v[0:3], v[198:201], v[104:107], v[0:3]
	v_mfma_f32_16x16x32_bf16 v[164:167], v[194:197], v[100:103], v[12:15]
	v_mfma_f32_16x16x32_bf16 v[168:171], v[194:197], v[108:111], v[8:11]
	v_mfma_f32_16x16x32_bf16 v[190:193], v[202:205], v[100:103], v[4:7]
	v_mfma_f32_16x16x32_bf16 v[194:197], v[202:205], v[108:111], v[0:3]
	s_barrier
	s_nop 1
	ds_read_b128 v[0:3], v160
	ds_read_b128 v[4:7], v160 offset:1024
	ds_read_b128 v[198:201], v160 offset:2048
	ds_read_b128 v[202:205], v160 offset:3072
	ds_read_b128 v[8:11], v153 offset:32768
	ds_read_b128 v[12:15], v153 offset:33792
	ds_read_b128 v[32:35], v154 offset:32768
	ds_read_b128 v[36:39], v154 offset:33792
	ds_read_b128 v[40:43], v162 offset:32768
	ds_read_b128 v[44:47], v162 offset:33792
	ds_read_b128 v[234:237], v163 offset:32768
	ds_read_b128 v[238:241], v163 offset:33792
	s_waitcnt vmcnt(2)
	s_barrier
	s_waitcnt lgkmcnt(0)
	v_mfma_f32_16x16x32_bf16 v[64:67], v[8:11], v[0:3], v[124:127]
	v_mfma_f32_16x16x32_bf16 v[104:107], v[12:15], v[4:7], v[64:67]
	v_mfma_f32_16x16x32_bf16 v[64:67], v[8:11], v[198:201], v[120:123]
	v_mfma_f32_16x16x32_bf16 v[108:111], v[12:15], v[202:205], v[64:67]
	v_mfma_f32_16x16x32_bf16 v[64:67], v[32:35], v[0:3], v[116:119]
	v_mfma_f32_16x16x32_bf16 v[96:99], v[36:39], v[4:7], v[64:67]
	v_mfma_f32_16x16x32_bf16 v[64:67], v[32:35], v[198:201], v[112:115]
	v_mfma_f32_16x16x32_bf16 v[100:103], v[36:39], v[202:205], v[64:67]
	v_mfma_f32_16x16x32_bf16 v[64:67], v[40:43], v[0:3], v[206:209]
	v_mfma_f32_16x16x32_bf16 v[72:75], v[44:47], v[4:7], v[64:67]
	v_mfma_f32_16x16x32_bf16 v[64:67], v[40:43], v[198:201], v[210:213]
	v_mfma_f32_16x16x32_bf16 v[76:79], v[44:47], v[202:205], v[64:67]
	v_mfma_f32_16x16x32_bf16 v[64:67], v[234:237], v[0:3], v[214:217]
	v_mfma_f32_16x16x32_bf16 v[68:71], v[234:237], v[198:201], v[218:221]
	v_mfma_f32_16x16x32_bf16 v[64:67], v[238:241], v[4:7], v[64:67]
	v_mfma_f32_16x16x32_bf16 v[68:71], v[238:241], v[202:205], v[68:71]
	s_barrier
	ds_read_b128 v[206:209], v161
	ds_read_b128 v[210:213], v161 offset:1024
	ds_read_b128 v[214:217], v161 offset:2048
	ds_read_b128 v[218:221], v161 offset:3072
	s_waitcnt vmcnt(0)
	s_barrier
	s_waitcnt lgkmcnt(0)
	v_mfma_f32_16x16x32_bf16 v[92:95], v[8:11], v[206:209], v[92:95]
	v_mfma_f32_16x16x32_bf16 v[8:11], v[8:11], v[214:217], v[88:91]
	v_mfma_f32_16x16x32_bf16 v[124:127], v[12:15], v[218:221], v[8:11]
	v_mfma_f32_16x16x32_bf16 v[8:11], v[32:35], v[206:209], v[84:87]
	v_mfma_f32_16x16x32_bf16 v[112:115], v[36:39], v[210:213], v[8:11]
	v_mfma_f32_16x16x32_bf16 v[8:11], v[32:35], v[214:217], v[80:83]
	v_mfma_f32_16x16x32_bf16 v[116:119], v[36:39], v[218:221], v[8:11]
	v_mfma_f32_16x16x32_bf16 v[8:11], v[40:43], v[206:209], v[174:177]
	v_mfma_f32_16x16x32_bf16 v[88:91], v[44:47], v[210:213], v[8:11]
	v_mfma_f32_16x16x32_bf16 v[8:11], v[40:43], v[214:217], v[178:181]
	v_mfma_f32_16x16x32_bf16 v[120:123], v[12:15], v[210:213], v[92:95]
	v_mfma_f32_16x16x32_bf16 v[92:95], v[44:47], v[218:221], v[8:11]
	v_mfma_f32_16x16x32_bf16 v[8:11], v[234:237], v[206:209], v[182:185]
	v_mfma_f32_16x16x32_bf16 v[80:83], v[238:241], v[210:213], v[8:11]
	v_mfma_f32_16x16x32_bf16 v[8:11], v[234:237], v[214:217], v[186:189]
	v_mfma_f32_16x16x32_bf16 v[84:87], v[238:241], v[218:221], v[8:11]
	s_barrier
	ds_read_b128 v[172:175], v153 offset:49152
	ds_read_b128 v[176:179], v153 offset:50176
	ds_read_b128 v[180:183], v154 offset:49152
	ds_read_b128 v[184:187], v154 offset:50176
	ds_read_b128 v[234:237], v162 offset:49152
	ds_read_b128 v[238:241], v162 offset:50176
	ds_read_b128 v[242:245], v163 offset:49152
	ds_read_b128 v[246:249], v163 offset:50176
	s_barrier
	s_waitcnt lgkmcnt(0)
	v_mfma_f32_16x16x32_bf16 v[8:11], v[172:175], v[0:3], v[60:63]
	v_mfma_f32_16x16x32_bf16 v[40:43], v[176:179], v[4:7], v[8:11]
	v_mfma_f32_16x16x32_bf16 v[8:11], v[172:175], v[198:201], v[56:59]
	v_mfma_f32_16x16x32_bf16 v[44:47], v[176:179], v[202:205], v[8:11]
	v_mfma_f32_16x16x32_bf16 v[8:11], v[180:183], v[0:3], v[52:55]
	v_mfma_f32_16x16x32_bf16 v[32:35], v[184:187], v[4:7], v[8:11]
	v_mfma_f32_16x16x32_bf16 v[8:11], v[180:183], v[198:201], v[48:51]
	v_mfma_f32_16x16x32_bf16 v[36:39], v[184:187], v[202:205], v[8:11]
	v_mfma_f32_16x16x32_bf16 v[8:11], v[234:237], v[0:3], v[226:229]
	v_mfma_f32_16x16x32_bf16 v[0:3], v[242:245], v[0:3], v[132:135]
	v_mfma_f32_16x16x32_bf16 v[8:11], v[238:241], v[4:7], v[8:11]
	v_mfma_f32_16x16x32_bf16 v[12:15], v[234:237], v[198:201], v[230:233]
	v_mfma_f32_16x16x32_bf16 v[0:3], v[246:249], v[4:7], v[0:3]
	v_mfma_f32_16x16x32_bf16 v[4:7], v[242:245], v[198:201], v[136:139]
	v_mfma_f32_16x16x32_bf16 v[12:15], v[238:241], v[202:205], v[12:15]
	v_mfma_f32_16x16x32_bf16 v[4:7], v[246:249], v[202:205], v[4:7]
	v_mfma_f32_16x16x32_bf16 v[16:19], v[180:183], v[214:217], v[16:19]
	v_mfma_f32_16x16x32_bf16 v[24:27], v[172:175], v[214:217], v[24:27]
	v_mfma_f32_16x16x32_bf16 v[52:55], v[184:187], v[218:221], v[16:19]
	v_mfma_f32_16x16x32_bf16 v[16:19], v[234:237], v[206:209], v[164:167]
	v_mfma_f32_16x16x32_bf16 v[28:31], v[172:175], v[206:209], v[28:31]
	v_mfma_f32_16x16x32_bf16 v[60:63], v[176:179], v[218:221], v[24:27]
	v_mfma_f32_16x16x32_bf16 v[20:23], v[180:183], v[206:209], v[20:23]
	v_mfma_f32_16x16x32_bf16 v[24:27], v[238:241], v[210:213], v[16:19]
	v_mfma_f32_16x16x32_bf16 v[16:19], v[234:237], v[214:217], v[168:171]
	v_mfma_f32_16x16x32_bf16 v[56:59], v[176:179], v[210:213], v[28:31]
	v_mfma_f32_16x16x32_bf16 v[48:51], v[184:187], v[210:213], v[20:23]
	v_mfma_f32_16x16x32_bf16 v[28:31], v[238:241], v[218:221], v[16:19]
	v_mfma_f32_16x16x32_bf16 v[16:19], v[242:245], v[206:209], v[190:193]
	v_mfma_f32_16x16x32_bf16 v[20:23], v[242:245], v[214:217], v[194:197]
	v_mfma_f32_16x16x32_bf16 v[16:19], v[246:249], v[210:213], v[16:19]
	v_mfma_f32_16x16x32_bf16 v[20:23], v[246:249], v[218:221], v[20:23]
	s_andn2_b64 vcc, exec, s[4:5]
	s_barrier
	s_cbranch_vccnz .LBB0_1463
	s_barrier
	s_branch .LBB0_1463
